# GEMM K-loops P1/P3/P4/P5: static s_setprio 1 for the trailing wave half (waves 4-7) at loop entry, reset after the back edge
# speedup vs baseline: 1.0013x; 1.0008x over previous
.LBB0_175:
	s_mov_b32 s28, s29
	s_ashr_i32 s29, s29, 31
	s_lshl_b64 s[34:35], s[28:29], 20
	s_add_u32 s34, s90, s34
	s_addc_u32 s35, s91, s35
	s_and_b64 s[36:37], s[30:31], exec
	s_mov_b32 s26, s27
	s_cselect_b32 s2, s35, s43
	s_cselect_b32 s29, s34, s42
	s_ashr_i32 s27, s27, 31
	s_lshl_b64 s[36:37], s[26:27], 20
	s_add_u32 s36, s92, s36
	s_addc_u32 s37, s93, s37
	s_and_b64 s[44:45], s[30:31], exec
	s_cselect_b32 s27, s37, s41
	s_cselect_b32 s39, s36, s40
	s_add_u32 s46, s40, 0x100
	s_addc_u32 s47, s41, 0
	s_add_u32 s40, s42, 0x80080
	v_mov_b32_e32 v2, 0
	s_addc_u32 s41, s43, 0
	s_mov_b32 s52, -2
	v_mov_b32_e32 v3, v2
	v_mov_b64_e32 v[4:5], v[2:3]
	v_mov_b64_e32 v[6:7], v[2:3]
	v_mov_b64_e32 v[8:9], v[2:3]
	v_mov_b64_e32 v[18:19], v[2:3]
	v_mov_b64_e32 v[20:21], v[2:3]
	v_mov_b64_e32 v[22:23], v[2:3]
	v_mov_b64_e32 v[24:25], v[2:3]
	v_mov_b64_e32 v[34:35], v[2:3]
	v_mov_b64_e32 v[36:37], v[2:3]
	v_mov_b64_e32 v[38:39], v[2:3]
	v_mov_b64_e32 v[40:41], v[2:3]
	v_mov_b64_e32 v[50:51], v[2:3]
	v_mov_b64_e32 v[52:53], v[2:3]
	v_mov_b64_e32 v[54:55], v[2:3]
	v_mov_b64_e32 v[56:57], v[2:3]
	v_mov_b64_e32 v[10:11], v[2:3]
	v_mov_b64_e32 v[12:13], v[2:3]
	v_mov_b64_e32 v[14:15], v[2:3]
	v_mov_b64_e32 v[16:17], v[2:3]
	v_mov_b64_e32 v[26:27], v[2:3]
	v_mov_b64_e32 v[28:29], v[2:3]
	v_mov_b64_e32 v[30:31], v[2:3]
	v_mov_b64_e32 v[32:33], v[2:3]
	v_mov_b64_e32 v[42:43], v[2:3]
	v_mov_b64_e32 v[44:45], v[2:3]
	v_mov_b64_e32 v[46:47], v[2:3]
	v_mov_b64_e32 v[48:49], v[2:3]
	v_mov_b64_e32 v[66:67], v[2:3]
	v_mov_b64_e32 v[68:69], v[2:3]
	v_mov_b64_e32 v[70:71], v[2:3]
	v_mov_b64_e32 v[72:73], v[2:3]
	v_mov_b64_e32 v[74:75], v[2:3]
	v_mov_b64_e32 v[76:77], v[2:3]
	v_mov_b64_e32 v[86:87], v[2:3]
	v_mov_b64_e32 v[88:89], v[2:3]
	v_mov_b64_e32 v[98:99], v[2:3]
	v_mov_b64_e32 v[100:101], v[2:3]
	v_mov_b64_e32 v[110:111], v[2:3]
	v_mov_b64_e32 v[112:113], v[2:3]
	v_mov_b64_e32 v[130:131], v[2:3]
	v_mov_b64_e32 v[132:133], v[2:3]
	v_mov_b64_e32 v[134:135], v[2:3]
	v_mov_b64_e32 v[136:137], v[2:3]
	v_mov_b64_e32 v[154:155], v[2:3]
	v_mov_b64_e32 v[156:157], v[2:3]
	v_mov_b64_e32 v[158:159], v[2:3]
	v_mov_b64_e32 v[160:161], v[2:3]
	v_mov_b64_e32 v[90:91], v[2:3]
	v_mov_b64_e32 v[92:93], v[2:3]
	v_mov_b64_e32 v[94:95], v[2:3]
	v_mov_b64_e32 v[96:97], v[2:3]
	v_mov_b64_e32 v[114:115], v[2:3]
	v_mov_b64_e32 v[116:117], v[2:3]
	v_mov_b64_e32 v[118:119], v[2:3]
	v_mov_b64_e32 v[120:121], v[2:3]
	v_mov_b64_e32 v[138:139], v[2:3]
	v_mov_b64_e32 v[140:141], v[2:3]
	v_mov_b64_e32 v[142:143], v[2:3]
	v_mov_b64_e32 v[144:145], v[2:3]
	v_mov_b64_e32 v[162:163], v[2:3]
	v_mov_b64_e32 v[164:165], v[2:3]
	v_mov_b64_e32 v[166:167], v[2:3]
	v_mov_b64_e32 v[168:169], v[2:3]
	v_add_u32_e32 v212, 0x18000, v218
	v_add_u32_e32 v213, 0x1c000, v218
	s_cmp_eq_u64 s[24:25], 0
	s_cbranch_scc0 .Lhp_skip_1
	s_setprio 1
.Lhp_skip_1:
.LBB0_176:
	ds_read_b128 v[58:61], v219
	ds_read_b128 v[62:65], v219 offset:1024
	ds_read_b128 v[78:81], v219 offset:2048
	ds_read_b128 v[82:85], v219 offset:3072
	ds_read_b128 v[102:105], v220
	ds_read_b128 v[106:109], v220 offset:1024
	ds_read_b128 v[122:125], v220 offset:2048
	ds_read_b128 v[126:129], v220 offset:3072
	s_add_u32 s42, s40, 0xfff80080
	s_addc_u32 s43, s41, -1
	s_cmp_eq_u32 s52, 28
	s_cselect_b32 s45, s2, s43
	s_cselect_b32 s44, s29, s42
	s_cselect_b32 s43, s27, s47
	s_cselect_b32 s42, s39, s46
	s_add_i32 m0, s49, 0xc000
	ds_read_b128 v[146:149], v221
	ds_read_b128 v[150:153], v221 offset:1024
	ds_read_b128 v[170:173], v221 offset:2048
	ds_read_b128 v[174:177], v221 offset:3072
	ds_read_b128 v[178:181], v221 offset:4096
	ds_read_b128 v[182:185], v221 offset:5120
	ds_read_b128 v[186:189], v221 offset:6144
	ds_read_b128 v[190:193], v221 offset:7168
	global_load_lds_dwordx4 v206, s[40:41]
	s_add_i32 m0, s49, 0xe000
	s_nop 0
	global_load_lds_dwordx4 v208, s[40:41]
	s_waitcnt vmcnt(8) lgkmcnt(0)
	s_barrier
	v_mfma_f32_16x16x32_bf16 v[166:169], v[58:61], v[146:149], v[166:169]
	v_mfma_f32_16x16x32_bf16 v[162:165], v[78:81], v[146:149], v[162:165]
	v_mfma_f32_16x16x32_bf16 v[142:145], v[58:61], v[170:173], v[142:145]
	v_mfma_f32_16x16x32_bf16 v[138:141], v[78:81], v[170:173], v[138:141]
	v_mfma_f32_16x16x32_bf16 v[118:121], v[58:61], v[178:181], v[118:121]
	v_mfma_f32_16x16x32_bf16 v[114:117], v[78:81], v[178:181], v[114:117]
	v_mfma_f32_16x16x32_bf16 v[94:97], v[58:61], v[186:189], v[94:97]
	v_mfma_f32_16x16x32_bf16 v[90:93], v[78:81], v[186:189], v[90:93]
	v_mfma_f32_16x16x32_bf16 v[166:169], v[62:65], v[150:153], v[166:169]
	v_mfma_f32_16x16x32_bf16 v[162:165], v[82:85], v[150:153], v[162:165]
	v_mfma_f32_16x16x32_bf16 v[142:145], v[62:65], v[174:177], v[142:145]
	v_mfma_f32_16x16x32_bf16 v[138:141], v[82:85], v[174:177], v[138:141]
	v_mfma_f32_16x16x32_bf16 v[118:121], v[62:65], v[182:185], v[118:121]
	v_mfma_f32_16x16x32_bf16 v[114:117], v[82:85], v[182:185], v[114:117]
	v_mfma_f32_16x16x32_bf16 v[94:97], v[62:65], v[190:193], v[94:97]
	v_mfma_f32_16x16x32_bf16 v[90:93], v[82:85], v[190:193], v[90:93]
	v_mfma_f32_16x16x32_bf16 v[158:161], v[102:105], v[146:149], v[158:161]
	v_mfma_f32_16x16x32_bf16 v[134:137], v[102:105], v[170:173], v[134:137]
	v_mfma_f32_16x16x32_bf16 v[130:133], v[122:125], v[170:173], v[130:133]
	v_mfma_f32_16x16x32_bf16 v[110:113], v[102:105], v[178:181], v[110:113]
	v_mfma_f32_16x16x32_bf16 v[98:101], v[122:125], v[178:181], v[98:101]
	v_mfma_f32_16x16x32_bf16 v[86:89], v[102:105], v[186:189], v[86:89]
	v_mfma_f32_16x16x32_bf16 v[74:77], v[122:125], v[186:189], v[74:77]
	v_mfma_f32_16x16x32_bf16 v[158:161], v[106:109], v[150:153], v[158:161]
	v_mfma_f32_16x16x32_bf16 v[146:149], v[122:125], v[146:149], v[154:157]
	v_mfma_f32_16x16x32_bf16 v[134:137], v[106:109], v[174:177], v[134:137]
	v_mfma_f32_16x16x32_bf16 v[130:133], v[126:129], v[174:177], v[130:133]
	v_mfma_f32_16x16x32_bf16 v[110:113], v[106:109], v[182:185], v[110:113]
	v_mfma_f32_16x16x32_bf16 v[98:101], v[126:129], v[182:185], v[98:101]
	v_mfma_f32_16x16x32_bf16 v[86:89], v[106:109], v[190:193], v[86:89]
	v_mfma_f32_16x16x32_bf16 v[74:77], v[126:129], v[190:193], v[74:77]
	v_mfma_f32_16x16x32_bf16 v[146:149], v[126:129], v[150:153], v[146:149]
	s_barrier
	s_add_i32 m0, s48, 0x10000
	ds_read_b128 v[150:153], v221 offset:16384
	ds_read_b128 v[154:157], v221 offset:17408
	ds_read_b128 v[170:173], v221 offset:18432
	ds_read_b128 v[174:177], v221 offset:19456
	ds_read_b128 v[178:181], v221 offset:20480
	ds_read_b128 v[182:185], v221 offset:21504
	ds_read_b128 v[186:189], v221 offset:22528
	ds_read_b128 v[190:193], v221 offset:23552
	global_load_lds_dwordx4 v198, s[42:43]
	s_add_i32 m0, s48, 0x12000
	s_add_u32 s54, s42, 0x80000
	s_addc_u32 s55, s43, 0
	global_load_lds_dwordx4 v202, s[42:43]
	s_add_i32 m0, s48, 0x14000
	s_nop 0
	global_load_lds_dwordx4 v198, s[54:55]
	s_add_i32 m0, s48, 0x16000
	s_nop 0
	global_load_lds_dwordx4 v202, s[54:55]
	s_mov_b32 m0, s49
	s_nop 0
	global_load_lds_dwordx4 v196, s[44:45]
	s_mov_b32 m0, s50
	s_nop 0
	global_load_lds_dwordx4 v200, s[44:45]
	s_waitcnt vmcnt(8) lgkmcnt(0)
	s_barrier
	v_mfma_f32_16x16x32_bf16 v[70:73], v[58:61], v[150:153], v[70:73]
	v_mfma_f32_16x16x32_bf16 v[66:69], v[78:81], v[150:153], v[66:69]
	v_mfma_f32_16x16x32_bf16 v[46:49], v[58:61], v[170:173], v[46:49]
	v_mfma_f32_16x16x32_bf16 v[42:45], v[78:81], v[170:173], v[42:45]
	v_mfma_f32_16x16x32_bf16 v[30:33], v[58:61], v[178:181], v[30:33]
	v_mfma_f32_16x16x32_bf16 v[26:29], v[78:81], v[178:181], v[26:29]
	v_mfma_f32_16x16x32_bf16 v[14:17], v[58:61], v[186:189], v[14:17]
	v_mfma_f32_16x16x32_bf16 v[10:13], v[78:81], v[186:189], v[10:13]
	v_mfma_f32_16x16x32_bf16 v[70:73], v[62:65], v[154:157], v[70:73]
	v_mfma_f32_16x16x32_bf16 v[66:69], v[82:85], v[154:157], v[66:69]
	v_mfma_f32_16x16x32_bf16 v[46:49], v[62:65], v[174:177], v[46:49]
	v_mfma_f32_16x16x32_bf16 v[42:45], v[82:85], v[174:177], v[42:45]
	v_mfma_f32_16x16x32_bf16 v[30:33], v[62:65], v[182:185], v[30:33]
	v_mfma_f32_16x16x32_bf16 v[26:29], v[82:85], v[182:185], v[26:29]
	v_mfma_f32_16x16x32_bf16 v[14:17], v[62:65], v[190:193], v[14:17]
	v_mfma_f32_16x16x32_bf16 v[10:13], v[82:85], v[190:193], v[10:13]
	v_mfma_f32_16x16x32_bf16 v[54:57], v[102:105], v[150:153], v[54:57]
	v_mfma_f32_16x16x32_bf16 v[50:53], v[122:125], v[150:153], v[50:53]
	v_mfma_f32_16x16x32_bf16 v[38:41], v[102:105], v[170:173], v[38:41]
	v_mfma_f32_16x16x32_bf16 v[34:37], v[122:125], v[170:173], v[34:37]
	v_mfma_f32_16x16x32_bf16 v[22:25], v[102:105], v[178:181], v[22:25]
	v_mfma_f32_16x16x32_bf16 v[18:21], v[122:125], v[178:181], v[18:21]
	v_mfma_f32_16x16x32_bf16 v[6:9], v[102:105], v[186:189], v[6:9]
	v_mfma_f32_16x16x32_bf16 v[2:5], v[122:125], v[186:189], v[2:5]
	v_mfma_f32_16x16x32_bf16 v[54:57], v[106:109], v[154:157], v[54:57]
	v_mfma_f32_16x16x32_bf16 v[50:53], v[126:129], v[154:157], v[50:53]
	v_mfma_f32_16x16x32_bf16 v[38:41], v[106:109], v[174:177], v[38:41]
	v_mfma_f32_16x16x32_bf16 v[34:37], v[126:129], v[174:177], v[34:37]
	v_mfma_f32_16x16x32_bf16 v[22:25], v[106:109], v[182:185], v[22:25]
	v_mfma_f32_16x16x32_bf16 v[18:21], v[126:129], v[182:185], v[18:21]
	v_mfma_f32_16x16x32_bf16 v[6:9], v[106:109], v[190:193], v[6:9]
	v_mfma_f32_16x16x32_bf16 v[2:5], v[126:129], v[190:193], v[2:5]
	s_barrier
	ds_read_b128 v[58:61], v212
	ds_read_b128 v[62:65], v212 offset:1024
	ds_read_b128 v[78:81], v212 offset:2048
	ds_read_b128 v[82:85], v212 offset:3072
	ds_read_b128 v[102:105], v213
	ds_read_b128 v[106:109], v213 offset:1024
	ds_read_b128 v[122:125], v213 offset:2048
	ds_read_b128 v[126:129], v213 offset:3072
	s_add_u32 s44, s44, 0x80000
	s_addc_u32 s45, s45, 0
	s_mov_b32 m0, s51
	ds_read_b128 v[150:153], v221 offset:32768
	ds_read_b128 v[154:157], v221 offset:33792
	ds_read_b128 v[170:173], v221 offset:34816
	ds_read_b128 v[174:177], v221 offset:35840
	ds_read_b128 v[178:181], v221 offset:36864
	ds_read_b128 v[182:185], v221 offset:37888
	ds_read_b128 v[186:189], v221 offset:38912
	ds_read_b128 v[190:193], v221 offset:39936
	global_load_lds_dwordx4 v196, s[44:45]
	s_mov_b32 m0, s72
	s_nop 0
	global_load_lds_dwordx4 v200, s[44:45]
	s_waitcnt vmcnt(8) lgkmcnt(0)
	s_barrier
	v_mfma_f32_16x16x32_bf16 v[166:169], v[58:61], v[150:153], v[166:169]
	v_mfma_f32_16x16x32_bf16 v[162:165], v[78:81], v[150:153], v[162:165]
	v_mfma_f32_16x16x32_bf16 v[142:145], v[58:61], v[170:173], v[142:145]
	v_mfma_f32_16x16x32_bf16 v[138:141], v[78:81], v[170:173], v[138:141]
	v_mfma_f32_16x16x32_bf16 v[118:121], v[58:61], v[178:181], v[118:121]
	v_mfma_f32_16x16x32_bf16 v[114:117], v[78:81], v[178:181], v[114:117]
	v_mfma_f32_16x16x32_bf16 v[94:97], v[58:61], v[186:189], v[94:97]
	v_mfma_f32_16x16x32_bf16 v[90:93], v[78:81], v[186:189], v[90:93]
	v_mfma_f32_16x16x32_bf16 v[166:169], v[62:65], v[154:157], v[166:169]
	v_mfma_f32_16x16x32_bf16 v[162:165], v[82:85], v[154:157], v[162:165]
	v_mfma_f32_16x16x32_bf16 v[142:145], v[62:65], v[174:177], v[142:145]
	v_mfma_f32_16x16x32_bf16 v[138:141], v[82:85], v[174:177], v[138:141]
	v_mfma_f32_16x16x32_bf16 v[118:121], v[62:65], v[182:185], v[118:121]
	v_mfma_f32_16x16x32_bf16 v[114:117], v[82:85], v[182:185], v[114:117]
	v_mfma_f32_16x16x32_bf16 v[94:97], v[62:65], v[190:193], v[94:97]
	v_mfma_f32_16x16x32_bf16 v[90:93], v[82:85], v[190:193], v[90:93]
	v_mfma_f32_16x16x32_bf16 v[158:161], v[102:105], v[150:153], v[158:161]
	v_mfma_f32_16x16x32_bf16 v[146:149], v[122:125], v[150:153], v[146:149]
	v_mfma_f32_16x16x32_bf16 v[134:137], v[102:105], v[170:173], v[134:137]
	v_mfma_f32_16x16x32_bf16 v[130:133], v[122:125], v[170:173], v[130:133]
	v_mfma_f32_16x16x32_bf16 v[110:113], v[102:105], v[178:181], v[110:113]
	v_mfma_f32_16x16x32_bf16 v[98:101], v[122:125], v[178:181], v[98:101]
	v_mfma_f32_16x16x32_bf16 v[86:89], v[102:105], v[186:189], v[86:89]
	v_mfma_f32_16x16x32_bf16 v[74:77], v[122:125], v[186:189], v[74:77]
	v_mfma_f32_16x16x32_bf16 v[158:161], v[106:109], v[154:157], v[158:161]
	v_mfma_f32_16x16x32_bf16 v[154:157], v[126:129], v[154:157], v[146:149]
	v_mfma_f32_16x16x32_bf16 v[134:137], v[106:109], v[174:177], v[134:137]
	v_mfma_f32_16x16x32_bf16 v[130:133], v[126:129], v[174:177], v[130:133]
	v_mfma_f32_16x16x32_bf16 v[110:113], v[106:109], v[182:185], v[110:113]
	v_mfma_f32_16x16x32_bf16 v[98:101], v[126:129], v[182:185], v[98:101]
	v_mfma_f32_16x16x32_bf16 v[86:89], v[106:109], v[190:193], v[86:89]
	v_mfma_f32_16x16x32_bf16 v[74:77], v[126:129], v[190:193], v[74:77]
	s_barrier
	s_add_u32 s98, s44, 0xfff80080
	s_addc_u32 s99, s45, -1
	s_add_i32 m0, s48, 0x18000
	ds_read_b128 v[146:149], v221 offset:49152
	ds_read_b128 v[150:153], v221 offset:50176
	ds_read_b128 v[170:173], v221 offset:51200
	ds_read_b128 v[174:177], v221 offset:52224
	ds_read_b128 v[178:181], v221 offset:53248
	ds_read_b128 v[182:185], v221 offset:54272
	ds_read_b128 v[186:189], v221 offset:55296
	ds_read_b128 v[190:193], v221 offset:56320
	s_add_u32 s100, s42, 0x80
	s_addc_u32 s101, s43, 0
	global_load_lds_dwordx4 v198, s[100:101]
	s_add_i32 m0, s48, 0x1a000
	s_add_u32 s42, s42, 0x80080
	s_addc_u32 s43, s43, 0
	global_load_lds_dwordx4 v202, s[100:101]
	s_add_i32 m0, s48, 0x1c000
	s_nop 0
	global_load_lds_dwordx4 v198, s[42:43]
	s_add_i32 m0, s48, 0x1e000
	s_nop 0
	global_load_lds_dwordx4 v202, s[42:43]
	s_mov_b32 m0, s79
	s_nop 0
	global_load_lds_dwordx4 v196, s[98:99]
	s_mov_b32 m0, s80
	s_nop 0
	global_load_lds_dwordx4 v200, s[98:99]
	s_waitcnt vmcnt(8) lgkmcnt(0)
	s_barrier
	v_mfma_f32_16x16x32_bf16 v[70:73], v[58:61], v[146:149], v[70:73]
	v_mfma_f32_16x16x32_bf16 v[66:69], v[78:81], v[146:149], v[66:69]
	v_mfma_f32_16x16x32_bf16 v[46:49], v[58:61], v[170:173], v[46:49]
	v_mfma_f32_16x16x32_bf16 v[42:45], v[78:81], v[170:173], v[42:45]
	v_mfma_f32_16x16x32_bf16 v[30:33], v[58:61], v[178:181], v[30:33]
	v_mfma_f32_16x16x32_bf16 v[26:29], v[78:81], v[178:181], v[26:29]
	v_mfma_f32_16x16x32_bf16 v[14:17], v[58:61], v[186:189], v[14:17]
	v_mfma_f32_16x16x32_bf16 v[10:13], v[78:81], v[186:189], v[10:13]
	v_mfma_f32_16x16x32_bf16 v[70:73], v[62:65], v[150:153], v[70:73]
	v_mfma_f32_16x16x32_bf16 v[66:69], v[82:85], v[150:153], v[66:69]
	v_mfma_f32_16x16x32_bf16 v[46:49], v[62:65], v[174:177], v[46:49]
	v_mfma_f32_16x16x32_bf16 v[42:45], v[82:85], v[174:177], v[42:45]
	v_mfma_f32_16x16x32_bf16 v[30:33], v[62:65], v[182:185], v[30:33]
	v_mfma_f32_16x16x32_bf16 v[26:29], v[82:85], v[182:185], v[26:29]
	v_mfma_f32_16x16x32_bf16 v[14:17], v[62:65], v[190:193], v[14:17]
	v_mfma_f32_16x16x32_bf16 v[10:13], v[82:85], v[190:193], v[10:13]
	v_mfma_f32_16x16x32_bf16 v[54:57], v[102:105], v[146:149], v[54:57]
	v_mfma_f32_16x16x32_bf16 v[50:53], v[122:125], v[146:149], v[50:53]
	v_mfma_f32_16x16x32_bf16 v[38:41], v[102:105], v[170:173], v[38:41]
	v_mfma_f32_16x16x32_bf16 v[34:37], v[122:125], v[170:173], v[34:37]
	v_mfma_f32_16x16x32_bf16 v[22:25], v[102:105], v[178:181], v[22:25]
	v_mfma_f32_16x16x32_bf16 v[18:21], v[122:125], v[178:181], v[18:21]
	v_mfma_f32_16x16x32_bf16 v[6:9], v[102:105], v[186:189], v[6:9]
	v_mfma_f32_16x16x32_bf16 v[2:5], v[122:125], v[186:189], v[2:5]
	v_mfma_f32_16x16x32_bf16 v[54:57], v[106:109], v[150:153], v[54:57]
	v_mfma_f32_16x16x32_bf16 v[50:53], v[126:129], v[150:153], v[50:53]
	v_mfma_f32_16x16x32_bf16 v[38:41], v[106:109], v[174:177], v[38:41]
	v_mfma_f32_16x16x32_bf16 v[34:37], v[126:129], v[174:177], v[34:37]
	v_mfma_f32_16x16x32_bf16 v[22:25], v[106:109], v[182:185], v[22:25]
	v_mfma_f32_16x16x32_bf16 v[18:21], v[126:129], v[182:185], v[18:21]
	v_mfma_f32_16x16x32_bf16 v[6:9], v[106:109], v[190:193], v[6:9]
	v_mfma_f32_16x16x32_bf16 v[2:5], v[126:129], v[190:193], v[2:5]
	s_barrier
	s_add_i32 s52, s52, 2
	s_add_u32 s46, s46, 0x100
	s_addc_u32 s47, s47, 0
	s_add_u32 s40, s40, 0x100
	s_addc_u32 s41, s41, 0
	s_cmp_gt_u32 s52, 29
	s_cbranch_scc0 .LBB0_176
	s_setprio 0
	s_and_b64 vcc, exec, s[24:25]
	s_cbranch_vccz .LBB0_179
	s_barrier

.LBB0_650:
	s_ashr_i32 s15, s14, 31
	s_lshl_b64 s[18:19], s[14:15], 20
	s_add_u32 s18, s92, s18
	s_addc_u32 s19, s93, s19
	s_and_b64 s[20:21], s[16:17], exec
	s_cselect_b32 s15, s19, s29
	s_cselect_b32 s23, s18, s28
	s_ashr_i32 s13, s12, 31
	s_lshl_b64 s[20:21], s[12:13], 20
	s_add_u32 s20, s94, s20
	s_addc_u32 s21, s95, s21
	s_and_b64 s[30:31], s[16:17], exec
	s_cselect_b32 s13, s21, s27
	s_cselect_b32 s43, s20, s26
	s_add_u32 s44, s26, 0x100
	s_addc_u32 s45, s27, 0
	s_add_u32 s26, s28, 0x80080
	v_mov_b32_e32 v2, 0
	s_addc_u32 s27, s29, 0
	s_mov_b32 s46, -2
	s_waitcnt lgkmcnt(0)
	v_mov_b32_e32 v3, v2
	v_mov_b64_e32 v[4:5], v[2:3]
	v_mov_b64_e32 v[6:7], v[2:3]
	v_mov_b64_e32 v[8:9], v[2:3]
	v_mov_b64_e32 v[18:19], v[2:3]
	v_mov_b64_e32 v[20:21], v[2:3]
	v_mov_b64_e32 v[22:23], v[2:3]
	v_mov_b64_e32 v[24:25], v[2:3]
	v_mov_b64_e32 v[34:35], v[2:3]
	v_mov_b64_e32 v[36:37], v[2:3]
	v_mov_b64_e32 v[38:39], v[2:3]
	v_mov_b64_e32 v[40:41], v[2:3]
	v_mov_b64_e32 v[50:51], v[2:3]
	v_mov_b64_e32 v[52:53], v[2:3]
	v_mov_b64_e32 v[54:55], v[2:3]
	v_mov_b64_e32 v[56:57], v[2:3]
	v_mov_b64_e32 v[10:11], v[2:3]
	v_mov_b64_e32 v[12:13], v[2:3]
	v_mov_b64_e32 v[14:15], v[2:3]
	v_mov_b64_e32 v[16:17], v[2:3]
	v_mov_b64_e32 v[26:27], v[2:3]
	v_mov_b64_e32 v[28:29], v[2:3]
	v_mov_b64_e32 v[30:31], v[2:3]
	v_mov_b64_e32 v[32:33], v[2:3]
	v_mov_b64_e32 v[42:43], v[2:3]
	v_mov_b64_e32 v[44:45], v[2:3]
	v_mov_b64_e32 v[46:47], v[2:3]
	v_mov_b64_e32 v[48:49], v[2:3]
	v_mov_b64_e32 v[58:59], v[2:3]
	v_mov_b64_e32 v[60:61], v[2:3]
	v_mov_b64_e32 v[62:63], v[2:3]
	v_mov_b64_e32 v[64:65], v[2:3]
	v_mov_b64_e32 v[66:67], v[2:3]
	v_mov_b64_e32 v[68:69], v[2:3]
	v_mov_b64_e32 v[70:71], v[2:3]
	v_mov_b64_e32 v[72:73], v[2:3]
	v_mov_b64_e32 v[82:83], v[2:3]
	v_mov_b64_e32 v[84:85], v[2:3]
	v_mov_b64_e32 v[86:87], v[2:3]
	v_mov_b64_e32 v[88:89], v[2:3]
	v_mov_b64_e32 v[98:99], v[2:3]
	v_mov_b64_e32 v[100:101], v[2:3]
	v_mov_b64_e32 v[102:103], v[2:3]
	v_mov_b64_e32 v[104:105], v[2:3]
	v_mov_b64_e32 v[114:115], v[2:3]
	v_mov_b64_e32 v[116:117], v[2:3]
	v_mov_b64_e32 v[118:119], v[2:3]
	v_mov_b64_e32 v[120:121], v[2:3]
	v_mov_b64_e32 v[74:75], v[2:3]
	v_mov_b64_e32 v[76:77], v[2:3]
	v_mov_b64_e32 v[78:79], v[2:3]
	v_mov_b64_e32 v[80:81], v[2:3]
	v_mov_b64_e32 v[90:91], v[2:3]
	v_mov_b64_e32 v[92:93], v[2:3]
	v_mov_b64_e32 v[94:95], v[2:3]
	v_mov_b64_e32 v[96:97], v[2:3]
	v_mov_b64_e32 v[106:107], v[2:3]
	v_mov_b64_e32 v[108:109], v[2:3]
	v_mov_b64_e32 v[110:111], v[2:3]
	v_mov_b64_e32 v[112:113], v[2:3]
	v_mov_b64_e32 v[122:123], v[2:3]
	v_mov_b64_e32 v[124:125], v[2:3]
	v_mov_b64_e32 v[126:127], v[2:3]
	v_mov_b64_e32 v[128:129], v[2:3]
	v_add_u32_e32 v192, 0x18000, v195
	v_add_u32_e32 v193, 0x1c000, v195
	s_cmp_eq_u64 s[10:11], 0
	s_cbranch_scc0 .Lhp_skip_3
	s_setprio 1
.Lhp_skip_3:
.LBB0_651:
	s_cmp_eq_u32 s46, 24
	s_cbranch_scc0 .Lp3pf_skip
	v_lshl_add_u32 v230, s24, 8, v1
	v_lshl_or_b32 v232, s22, 8, v196
	v_ashrrev_i32_e32 v233, 31, v232
	v_lshlrev_b64 v[232:233], 1, v[232:233]
	v_ashrrev_i32_e32 v231, 31, v230
	v_lshlrev_b64 v[230:231], 12, v[230:231]
	v_lshl_add_u64 v[232:233], s[90:91], 0, v[232:233]
	v_lshl_add_u64 v[230:231], v[232:233], 0, v[230:231]
	s_mov_b64 s[40:41], 0x10000
	v_lshl_add_u64 v[232:233], v[230:231], 0, s[40:41]
	global_load_dwordx2 v[234:235], v[232:233], off
	global_load_dwordx2 v[236:237], v[232:233], off offset:32
	global_load_dwordx2 v[238:239], v[232:233], off offset:256
	global_load_dwordx2 v[240:241], v[232:233], off offset:288
	s_mov_b64 s[40:41], 0x20000
	v_lshl_add_u64 v[232:233], v[230:231], 0, s[40:41]
	global_load_dwordx2 v[244:245], v[232:233], off
	global_load_dwordx2 v[246:247], v[232:233], off offset:32
	global_load_dwordx2 v[248:249], v[232:233], off offset:256
	global_load_dwordx2 v[250:251], v[232:233], off offset:288
	s_mov_b64 s[40:41], 0x30000
	v_lshl_add_u64 v[232:233], v[230:231], 0, s[40:41]
	global_load_dwordx2 v[252:253], v[232:233], off
	global_load_dwordx2 v[254:255], v[232:233], off offset:32
	global_load_dwordx2 v[230:231], v[232:233], off offset:256
	s_nop 0
	global_load_dwordx2 v[232:233], v[232:233], off offset:288
.Lp3pf_skip:
	ds_read_b128 v[140:143], v197
	ds_read_b128 v[144:147], v197 offset:1024
	ds_read_b128 v[148:151], v197 offset:2048
	ds_read_b128 v[152:155], v197 offset:3072
	ds_read_b128 v[156:159], v198
	ds_read_b128 v[160:163], v198 offset:1024
	ds_read_b128 v[164:167], v198 offset:2048
	ds_read_b128 v[168:171], v198 offset:3072
	s_add_u32 s28, s26, 0xfff80080
	s_addc_u32 s29, s27, -1
	s_cmp_eq_u32 s46, 28
	s_cselect_b32 s31, s15, s29
	s_cselect_b32 s30, s23, s28
	s_cselect_b32 s29, s13, s45
	s_cselect_b32 s28, s43, s44
	s_add_i32 m0, s25, 0xc000
	ds_read_b128 v[172:175], v199
	ds_read_b128 v[176:179], v199 offset:1024
	ds_read_b128 v[180:183], v199 offset:2048
	ds_read_b128 v[184:187], v199 offset:3072
	ds_read_b128 v[188:191], v199 offset:4096
	ds_read_b128 v[202:205], v199 offset:5120
	ds_read_b128 v[206:209], v199 offset:6144
	ds_read_b128 v[210:213], v199 offset:7168
	global_load_lds_dwordx4 v134, s[26:27]
	s_add_i32 m0, s25, 0xe000
	s_nop 0
	global_load_lds_dwordx4 v136, s[26:27]
	s_waitcnt vmcnt(8) lgkmcnt(0)
	s_barrier
	v_mfma_f32_16x16x32_bf16 v[126:129], v[140:143], v[172:175], v[126:129]
	v_mfma_f32_16x16x32_bf16 v[122:125], v[148:151], v[172:175], v[122:125]
	v_mfma_f32_16x16x32_bf16 v[110:113], v[140:143], v[180:183], v[110:113]
	v_mfma_f32_16x16x32_bf16 v[106:109], v[148:151], v[180:183], v[106:109]
	v_mfma_f32_16x16x32_bf16 v[94:97], v[140:143], v[188:191], v[94:97]
	v_mfma_f32_16x16x32_bf16 v[90:93], v[148:151], v[188:191], v[90:93]
	v_mfma_f32_16x16x32_bf16 v[78:81], v[140:143], v[206:209], v[78:81]
	v_mfma_f32_16x16x32_bf16 v[74:77], v[148:151], v[206:209], v[74:77]
	v_mfma_f32_16x16x32_bf16 v[126:129], v[144:147], v[176:179], v[126:129]
	v_mfma_f32_16x16x32_bf16 v[122:125], v[152:155], v[176:179], v[122:125]
	v_mfma_f32_16x16x32_bf16 v[110:113], v[144:147], v[184:187], v[110:113]
	v_mfma_f32_16x16x32_bf16 v[106:109], v[152:155], v[184:187], v[106:109]
	v_mfma_f32_16x16x32_bf16 v[94:97], v[144:147], v[202:205], v[94:97]
	v_mfma_f32_16x16x32_bf16 v[90:93], v[152:155], v[202:205], v[90:93]
	v_mfma_f32_16x16x32_bf16 v[78:81], v[144:147], v[210:213], v[78:81]
	v_mfma_f32_16x16x32_bf16 v[74:77], v[152:155], v[210:213], v[74:77]
	v_mfma_f32_16x16x32_bf16 v[118:121], v[156:159], v[172:175], v[118:121]
	v_mfma_f32_16x16x32_bf16 v[114:117], v[164:167], v[172:175], v[114:117]
	v_mfma_f32_16x16x32_bf16 v[102:105], v[156:159], v[180:183], v[102:105]
	v_mfma_f32_16x16x32_bf16 v[98:101], v[164:167], v[180:183], v[98:101]
	v_mfma_f32_16x16x32_bf16 v[86:89], v[156:159], v[188:191], v[86:89]
	v_mfma_f32_16x16x32_bf16 v[82:85], v[164:167], v[188:191], v[82:85]
	v_mfma_f32_16x16x32_bf16 v[70:73], v[156:159], v[206:209], v[70:73]
	v_mfma_f32_16x16x32_bf16 v[66:69], v[164:167], v[206:209], v[66:69]
	v_mfma_f32_16x16x32_bf16 v[118:121], v[160:163], v[176:179], v[118:121]
	v_mfma_f32_16x16x32_bf16 v[114:117], v[168:171], v[176:179], v[114:117]
	v_mfma_f32_16x16x32_bf16 v[102:105], v[160:163], v[184:187], v[102:105]
	v_mfma_f32_16x16x32_bf16 v[98:101], v[168:171], v[184:187], v[98:101]
	v_mfma_f32_16x16x32_bf16 v[86:89], v[160:163], v[202:205], v[86:89]
	v_mfma_f32_16x16x32_bf16 v[82:85], v[168:171], v[202:205], v[82:85]
	v_mfma_f32_16x16x32_bf16 v[70:73], v[160:163], v[210:213], v[70:73]
	v_mfma_f32_16x16x32_bf16 v[66:69], v[168:171], v[210:213], v[66:69]
	s_barrier
	s_add_i32 m0, s3, 0x10000
	ds_read_b128 v[172:175], v199 offset:16384
	ds_read_b128 v[176:179], v199 offset:17408
	ds_read_b128 v[180:183], v199 offset:18432
	ds_read_b128 v[184:187], v199 offset:19456
	ds_read_b128 v[188:191], v199 offset:20480
	ds_read_b128 v[202:205], v199 offset:21504
	ds_read_b128 v[206:209], v199 offset:22528
	ds_read_b128 v[210:213], v199 offset:23552
	global_load_lds_dwordx4 v130, s[28:29]
	s_add_i32 m0, s3, 0x12000
	s_add_u32 s48, s28, 0x80000
	s_addc_u32 s49, s29, 0
	global_load_lds_dwordx4 v132, s[28:29]
	s_add_i32 m0, s3, 0x14000
	s_nop 0
	global_load_lds_dwordx4 v130, s[48:49]
	s_add_i32 m0, s3, 0x16000
	s_nop 0
	global_load_lds_dwordx4 v132, s[48:49]
	s_mov_b32 m0, s25
	s_nop 0
	global_load_lds_dwordx4 v130, s[30:31]
	s_mov_b32 m0, s34
	s_nop 0
	global_load_lds_dwordx4 v132, s[30:31]
	s_waitcnt vmcnt(8) lgkmcnt(0)
	s_barrier
	v_mfma_f32_16x16x32_bf16 v[62:65], v[140:143], v[172:175], v[62:65]
	v_mfma_f32_16x16x32_bf16 v[58:61], v[148:151], v[172:175], v[58:61]
	v_mfma_f32_16x16x32_bf16 v[46:49], v[140:143], v[180:183], v[46:49]
	v_mfma_f32_16x16x32_bf16 v[42:45], v[148:151], v[180:183], v[42:45]
	v_mfma_f32_16x16x32_bf16 v[30:33], v[140:143], v[188:191], v[30:33]
	v_mfma_f32_16x16x32_bf16 v[26:29], v[148:151], v[188:191], v[26:29]
	v_mfma_f32_16x16x32_bf16 v[14:17], v[140:143], v[206:209], v[14:17]
	v_mfma_f32_16x16x32_bf16 v[10:13], v[148:151], v[206:209], v[10:13]
	v_mfma_f32_16x16x32_bf16 v[62:65], v[144:147], v[176:179], v[62:65]
	v_mfma_f32_16x16x32_bf16 v[58:61], v[152:155], v[176:179], v[58:61]
	v_mfma_f32_16x16x32_bf16 v[46:49], v[144:147], v[184:187], v[46:49]
	v_mfma_f32_16x16x32_bf16 v[42:45], v[152:155], v[184:187], v[42:45]
	v_mfma_f32_16x16x32_bf16 v[30:33], v[144:147], v[202:205], v[30:33]
	v_mfma_f32_16x16x32_bf16 v[26:29], v[152:155], v[202:205], v[26:29]
	v_mfma_f32_16x16x32_bf16 v[14:17], v[144:147], v[210:213], v[14:17]
	v_mfma_f32_16x16x32_bf16 v[10:13], v[152:155], v[210:213], v[10:13]
	v_mfma_f32_16x16x32_bf16 v[54:57], v[156:159], v[172:175], v[54:57]
	v_mfma_f32_16x16x32_bf16 v[50:53], v[164:167], v[172:175], v[50:53]
	v_mfma_f32_16x16x32_bf16 v[38:41], v[156:159], v[180:183], v[38:41]
	v_mfma_f32_16x16x32_bf16 v[34:37], v[164:167], v[180:183], v[34:37]
	v_mfma_f32_16x16x32_bf16 v[22:25], v[156:159], v[188:191], v[22:25]
	v_mfma_f32_16x16x32_bf16 v[18:21], v[164:167], v[188:191], v[18:21]
	v_mfma_f32_16x16x32_bf16 v[6:9], v[156:159], v[206:209], v[6:9]
	v_mfma_f32_16x16x32_bf16 v[2:5], v[164:167], v[206:209], v[2:5]
	v_mfma_f32_16x16x32_bf16 v[54:57], v[160:163], v[176:179], v[54:57]
	v_mfma_f32_16x16x32_bf16 v[50:53], v[168:171], v[176:179], v[50:53]
	v_mfma_f32_16x16x32_bf16 v[38:41], v[160:163], v[184:187], v[38:41]
	v_mfma_f32_16x16x32_bf16 v[34:37], v[168:171], v[184:187], v[34:37]
	v_mfma_f32_16x16x32_bf16 v[22:25], v[160:163], v[202:205], v[22:25]
	v_mfma_f32_16x16x32_bf16 v[18:21], v[168:171], v[202:205], v[18:21]
	v_mfma_f32_16x16x32_bf16 v[6:9], v[160:163], v[210:213], v[6:9]
	v_mfma_f32_16x16x32_bf16 v[2:5], v[168:171], v[210:213], v[2:5]
	s_barrier
	ds_read_b128 v[140:143], v192
	ds_read_b128 v[144:147], v192 offset:1024
	ds_read_b128 v[148:151], v192 offset:2048
	ds_read_b128 v[152:155], v192 offset:3072
	ds_read_b128 v[156:159], v193
	ds_read_b128 v[160:163], v193 offset:1024
	ds_read_b128 v[164:167], v193 offset:2048
	ds_read_b128 v[168:171], v193 offset:3072
	s_add_u32 s30, s30, 0x80000
	s_addc_u32 s31, s31, 0
	s_mov_b32 m0, s35
	ds_read_b128 v[172:175], v199 offset:32768
	ds_read_b128 v[176:179], v199 offset:33792
	ds_read_b128 v[180:183], v199 offset:34816
	ds_read_b128 v[184:187], v199 offset:35840
	ds_read_b128 v[188:191], v199 offset:36864
	ds_read_b128 v[202:205], v199 offset:37888
	ds_read_b128 v[206:209], v199 offset:38912
	ds_read_b128 v[210:213], v199 offset:39936
	global_load_lds_dwordx4 v130, s[30:31]
	s_mov_b32 m0, s36
	s_nop 0
	global_load_lds_dwordx4 v132, s[30:31]
	s_waitcnt vmcnt(8) lgkmcnt(0)
	s_barrier
	v_mfma_f32_16x16x32_bf16 v[126:129], v[140:143], v[172:175], v[126:129]
	v_mfma_f32_16x16x32_bf16 v[122:125], v[148:151], v[172:175], v[122:125]
	v_mfma_f32_16x16x32_bf16 v[110:113], v[140:143], v[180:183], v[110:113]
	v_mfma_f32_16x16x32_bf16 v[106:109], v[148:151], v[180:183], v[106:109]
	v_mfma_f32_16x16x32_bf16 v[94:97], v[140:143], v[188:191], v[94:97]
	v_mfma_f32_16x16x32_bf16 v[90:93], v[148:151], v[188:191], v[90:93]
	v_mfma_f32_16x16x32_bf16 v[78:81], v[140:143], v[206:209], v[78:81]
	v_mfma_f32_16x16x32_bf16 v[74:77], v[148:151], v[206:209], v[74:77]
	v_mfma_f32_16x16x32_bf16 v[126:129], v[144:147], v[176:179], v[126:129]
	v_mfma_f32_16x16x32_bf16 v[122:125], v[152:155], v[176:179], v[122:125]
	v_mfma_f32_16x16x32_bf16 v[110:113], v[144:147], v[184:187], v[110:113]
	v_mfma_f32_16x16x32_bf16 v[106:109], v[152:155], v[184:187], v[106:109]
	v_mfma_f32_16x16x32_bf16 v[94:97], v[144:147], v[202:205], v[94:97]
	v_mfma_f32_16x16x32_bf16 v[90:93], v[152:155], v[202:205], v[90:93]
	v_mfma_f32_16x16x32_bf16 v[78:81], v[144:147], v[210:213], v[78:81]
	v_mfma_f32_16x16x32_bf16 v[74:77], v[152:155], v[210:213], v[74:77]
	v_mfma_f32_16x16x32_bf16 v[118:121], v[156:159], v[172:175], v[118:121]
	v_mfma_f32_16x16x32_bf16 v[114:117], v[164:167], v[172:175], v[114:117]
	v_mfma_f32_16x16x32_bf16 v[102:105], v[156:159], v[180:183], v[102:105]
	v_mfma_f32_16x16x32_bf16 v[98:101], v[164:167], v[180:183], v[98:101]
	v_mfma_f32_16x16x32_bf16 v[86:89], v[156:159], v[188:191], v[86:89]
	v_mfma_f32_16x16x32_bf16 v[82:85], v[164:167], v[188:191], v[82:85]
	v_mfma_f32_16x16x32_bf16 v[70:73], v[156:159], v[206:209], v[70:73]
	v_mfma_f32_16x16x32_bf16 v[66:69], v[164:167], v[206:209], v[66:69]
	v_mfma_f32_16x16x32_bf16 v[118:121], v[160:163], v[176:179], v[118:121]
	v_mfma_f32_16x16x32_bf16 v[114:117], v[168:171], v[176:179], v[114:117]
	v_mfma_f32_16x16x32_bf16 v[102:105], v[160:163], v[184:187], v[102:105]
	v_mfma_f32_16x16x32_bf16 v[98:101], v[168:171], v[184:187], v[98:101]
	v_mfma_f32_16x16x32_bf16 v[86:89], v[160:163], v[202:205], v[86:89]
	v_mfma_f32_16x16x32_bf16 v[82:85], v[168:171], v[202:205], v[82:85]
	v_mfma_f32_16x16x32_bf16 v[70:73], v[160:163], v[210:213], v[70:73]
	v_mfma_f32_16x16x32_bf16 v[66:69], v[168:171], v[210:213], v[66:69]
	s_barrier
	s_add_u32 s98, s30, 0xfff80080
	s_addc_u32 s99, s31, -1
	s_add_i32 m0, s3, 0x18000
	ds_read_b128 v[172:175], v199 offset:49152
	ds_read_b128 v[176:179], v199 offset:50176
	ds_read_b128 v[180:183], v199 offset:51200
	ds_read_b128 v[184:187], v199 offset:52224
	ds_read_b128 v[188:191], v199 offset:53248
	ds_read_b128 v[202:205], v199 offset:54272
	ds_read_b128 v[206:209], v199 offset:55296
	ds_read_b128 v[210:213], v199 offset:56320
	s_add_u32 s100, s28, 0x80
	s_addc_u32 s101, s29, 0
	global_load_lds_dwordx4 v130, s[100:101]
	s_add_i32 m0, s3, 0x1a000
	s_add_u32 s28, s28, 0x80080
	s_addc_u32 s29, s29, 0
	global_load_lds_dwordx4 v132, s[100:101]
	s_add_i32 m0, s3, 0x1c000
	s_nop 0
	global_load_lds_dwordx4 v130, s[28:29]
	s_add_i32 m0, s3, 0x1e000
	s_nop 0
	global_load_lds_dwordx4 v132, s[28:29]
	s_mov_b32 m0, s38
	s_nop 0
	global_load_lds_dwordx4 v130, s[98:99]
	s_mov_b32 m0, s39
	s_nop 0
	global_load_lds_dwordx4 v132, s[98:99]
	s_waitcnt vmcnt(8) lgkmcnt(0)
	s_barrier
	v_mfma_f32_16x16x32_bf16 v[62:65], v[140:143], v[172:175], v[62:65]
	v_mfma_f32_16x16x32_bf16 v[58:61], v[148:151], v[172:175], v[58:61]
	v_mfma_f32_16x16x32_bf16 v[46:49], v[140:143], v[180:183], v[46:49]
	v_mfma_f32_16x16x32_bf16 v[42:45], v[148:151], v[180:183], v[42:45]
	v_mfma_f32_16x16x32_bf16 v[30:33], v[140:143], v[188:191], v[30:33]
	v_mfma_f32_16x16x32_bf16 v[26:29], v[148:151], v[188:191], v[26:29]
	v_mfma_f32_16x16x32_bf16 v[14:17], v[140:143], v[206:209], v[14:17]
	v_mfma_f32_16x16x32_bf16 v[10:13], v[148:151], v[206:209], v[10:13]
	v_mfma_f32_16x16x32_bf16 v[62:65], v[144:147], v[176:179], v[62:65]
	v_mfma_f32_16x16x32_bf16 v[58:61], v[152:155], v[176:179], v[58:61]
	v_mfma_f32_16x16x32_bf16 v[46:49], v[144:147], v[184:187], v[46:49]
	v_mfma_f32_16x16x32_bf16 v[42:45], v[152:155], v[184:187], v[42:45]
	v_mfma_f32_16x16x32_bf16 v[30:33], v[144:147], v[202:205], v[30:33]
	v_mfma_f32_16x16x32_bf16 v[26:29], v[152:155], v[202:205], v[26:29]
	v_mfma_f32_16x16x32_bf16 v[14:17], v[144:147], v[210:213], v[14:17]
	v_mfma_f32_16x16x32_bf16 v[10:13], v[152:155], v[210:213], v[10:13]
	v_mfma_f32_16x16x32_bf16 v[54:57], v[156:159], v[172:175], v[54:57]
	v_mfma_f32_16x16x32_bf16 v[50:53], v[164:167], v[172:175], v[50:53]
	v_mfma_f32_16x16x32_bf16 v[38:41], v[156:159], v[180:183], v[38:41]
	v_mfma_f32_16x16x32_bf16 v[34:37], v[164:167], v[180:183], v[34:37]
	v_mfma_f32_16x16x32_bf16 v[22:25], v[156:159], v[188:191], v[22:25]
	v_mfma_f32_16x16x32_bf16 v[18:21], v[164:167], v[188:191], v[18:21]
	v_mfma_f32_16x16x32_bf16 v[6:9], v[156:159], v[206:209], v[6:9]
	v_mfma_f32_16x16x32_bf16 v[2:5], v[164:167], v[206:209], v[2:5]
	v_mfma_f32_16x16x32_bf16 v[54:57], v[160:163], v[176:179], v[54:57]
	v_mfma_f32_16x16x32_bf16 v[50:53], v[168:171], v[176:179], v[50:53]
	v_mfma_f32_16x16x32_bf16 v[38:41], v[160:163], v[184:187], v[38:41]
	v_mfma_f32_16x16x32_bf16 v[34:37], v[168:171], v[184:187], v[34:37]
	v_mfma_f32_16x16x32_bf16 v[22:25], v[160:163], v[202:205], v[22:25]
	v_mfma_f32_16x16x32_bf16 v[18:21], v[168:171], v[202:205], v[18:21]
	v_mfma_f32_16x16x32_bf16 v[6:9], v[160:163], v[210:213], v[6:9]
	v_mfma_f32_16x16x32_bf16 v[2:5], v[168:171], v[210:213], v[2:5]
	s_barrier
	s_add_i32 s46, s46, 2
	s_add_u32 s44, s44, 0x100
	s_addc_u32 s45, s45, 0
	s_add_u32 s26, s26, 0x100
	s_addc_u32 s27, s27, 0
	s_cmp_gt_u32 s46, 29
	s_cbranch_scc0 .LBB0_651
	s_setprio 0
	s_and_b64 vcc, exec, s[10:11]
	s_cbranch_vccz .LBB0_654
	s_barrier

.LBB0_807:
	s_mov_b32 s18, s19
	s_ashr_i32 s19, s19, 31
	s_lshl_b64 s[22:23], s[18:19], 20
	s_add_u32 s22, s70, s22
	s_addc_u32 s23, s71, s23
	s_and_b64 s[24:25], s[20:21], exec
	s_mov_b32 s16, s17
	s_cselect_b32 s19, s23, s35
	s_cselect_b32 s51, s22, s34
	s_ashr_i32 s17, s17, 31
	s_lshl_b64 s[24:25], s[16:17], 20
	s_add_u32 s24, s84, s24
	s_addc_u32 s25, s85, s25
	s_and_b64 s[36:37], s[20:21], exec
	s_cselect_b32 s17, s25, s31
	s_cselect_b32 s52, s24, s30
	s_add_u32 s53, s30, 0x100
	s_addc_u32 s54, s31, 0
	s_add_u32 s30, s34, 0x80080
	v_mov_b32_e32 v2, 0
	s_addc_u32 s31, s35, 0
	s_mov_b32 s55, -2
	v_mov_b32_e32 v3, v2
	v_mov_b64_e32 v[4:5], v[2:3]
	v_mov_b64_e32 v[6:7], v[2:3]
	v_mov_b64_e32 v[8:9], v[2:3]
	v_mov_b64_e32 v[18:19], v[2:3]
	v_mov_b64_e32 v[20:21], v[2:3]
	v_mov_b64_e32 v[22:23], v[2:3]
	v_mov_b64_e32 v[24:25], v[2:3]
	v_mov_b64_e32 v[34:35], v[2:3]
	v_mov_b64_e32 v[36:37], v[2:3]
	v_mov_b64_e32 v[38:39], v[2:3]
	v_mov_b64_e32 v[40:41], v[2:3]
	v_mov_b64_e32 v[50:51], v[2:3]
	v_mov_b64_e32 v[52:53], v[2:3]
	v_mov_b64_e32 v[54:55], v[2:3]
	v_mov_b64_e32 v[56:57], v[2:3]
	v_mov_b64_e32 v[10:11], v[2:3]
	v_mov_b64_e32 v[12:13], v[2:3]
	v_mov_b64_e32 v[14:15], v[2:3]
	v_mov_b64_e32 v[16:17], v[2:3]
	v_mov_b64_e32 v[26:27], v[2:3]
	v_mov_b64_e32 v[28:29], v[2:3]
	v_mov_b64_e32 v[30:31], v[2:3]
	v_mov_b64_e32 v[32:33], v[2:3]
	v_mov_b64_e32 v[42:43], v[2:3]
	v_mov_b64_e32 v[44:45], v[2:3]
	v_mov_b64_e32 v[46:47], v[2:3]
	v_mov_b64_e32 v[48:49], v[2:3]
	v_mov_b64_e32 v[58:59], v[2:3]
	v_mov_b64_e32 v[60:61], v[2:3]
	v_mov_b64_e32 v[62:63], v[2:3]
	v_mov_b64_e32 v[64:65], v[2:3]
	v_mov_b64_e32 v[66:67], v[2:3]
	v_mov_b64_e32 v[68:69], v[2:3]
	v_mov_b64_e32 v[70:71], v[2:3]
	v_mov_b64_e32 v[72:73], v[2:3]
	v_mov_b64_e32 v[82:83], v[2:3]
	v_mov_b64_e32 v[84:85], v[2:3]
	v_mov_b64_e32 v[86:87], v[2:3]
	v_mov_b64_e32 v[88:89], v[2:3]
	v_mov_b64_e32 v[98:99], v[2:3]
	v_mov_b64_e32 v[100:101], v[2:3]
	v_mov_b64_e32 v[102:103], v[2:3]
	v_mov_b64_e32 v[104:105], v[2:3]
	v_mov_b64_e32 v[114:115], v[2:3]
	v_mov_b64_e32 v[116:117], v[2:3]
	v_mov_b64_e32 v[118:119], v[2:3]
	v_mov_b64_e32 v[120:121], v[2:3]
	v_mov_b64_e32 v[74:75], v[2:3]
	v_mov_b64_e32 v[76:77], v[2:3]
	v_mov_b64_e32 v[78:79], v[2:3]
	v_mov_b64_e32 v[80:81], v[2:3]
	v_mov_b64_e32 v[90:91], v[2:3]
	v_mov_b64_e32 v[92:93], v[2:3]
	v_mov_b64_e32 v[94:95], v[2:3]
	v_mov_b64_e32 v[96:97], v[2:3]
	v_mov_b64_e32 v[106:107], v[2:3]
	v_mov_b64_e32 v[108:109], v[2:3]
	v_mov_b64_e32 v[110:111], v[2:3]
	v_mov_b64_e32 v[112:113], v[2:3]
	v_mov_b64_e32 v[122:123], v[2:3]
	v_mov_b64_e32 v[124:125], v[2:3]
	v_mov_b64_e32 v[126:127], v[2:3]
	v_mov_b64_e32 v[128:129], v[2:3]
	v_add_u32_e32 v148, 0x18000, v150
	v_add_u32_e32 v149, 0x1c000, v150
	s_cmp_eq_u64 s[12:13], 0
	s_cbranch_scc0 .Lhp_skip_4
	s_setprio 1
.Lhp_skip_4:
.LBB0_808:
	ds_read_b128 v[144:147], v152
	ds_read_b128 v[156:159], v152 offset:1024
	ds_read_b128 v[160:163], v152 offset:2048
	ds_read_b128 v[164:167], v152 offset:3072
	ds_read_b128 v[168:171], v153
	ds_read_b128 v[172:175], v153 offset:1024
	ds_read_b128 v[176:179], v153 offset:2048
	ds_read_b128 v[180:183], v153 offset:3072
	s_add_u32 s34, s30, 0xfff80080
	s_addc_u32 s35, s31, -1
	s_cmp_eq_u32 s55, 28
	s_cselect_b32 s37, s19, s35
	s_cselect_b32 s36, s51, s34
	s_cselect_b32 s35, s17, s54
	s_cselect_b32 s34, s52, s53
	s_add_i32 m0, s27, 0xc000
	ds_read_b128 v[184:187], v154
	ds_read_b128 v[188:191], v154 offset:1024
	ds_read_b128 v[196:199], v154 offset:2048
	ds_read_b128 v[200:203], v154 offset:3072
	ds_read_b128 v[204:207], v154 offset:4096
	ds_read_b128 v[208:211], v154 offset:5120
	ds_read_b128 v[212:215], v154 offset:6144
	ds_read_b128 v[216:219], v154 offset:7168
	global_load_lds_dwordx4 v138, s[30:31]
	s_add_i32 m0, s27, 0xe000
	s_nop 0
	global_load_lds_dwordx4 v140, s[30:31]
	s_waitcnt vmcnt(8) lgkmcnt(0)
	s_barrier
	v_mfma_f32_16x16x32_bf16 v[126:129], v[144:147], v[184:187], v[126:129]
	v_mfma_f32_16x16x32_bf16 v[122:125], v[160:163], v[184:187], v[122:125]
	v_mfma_f32_16x16x32_bf16 v[110:113], v[144:147], v[196:199], v[110:113]
	v_mfma_f32_16x16x32_bf16 v[106:109], v[160:163], v[196:199], v[106:109]
	v_mfma_f32_16x16x32_bf16 v[94:97], v[144:147], v[204:207], v[94:97]
	v_mfma_f32_16x16x32_bf16 v[90:93], v[160:163], v[204:207], v[90:93]
	v_mfma_f32_16x16x32_bf16 v[78:81], v[144:147], v[212:215], v[78:81]
	v_mfma_f32_16x16x32_bf16 v[74:77], v[160:163], v[212:215], v[74:77]
	v_mfma_f32_16x16x32_bf16 v[126:129], v[156:159], v[188:191], v[126:129]
	v_mfma_f32_16x16x32_bf16 v[122:125], v[164:167], v[188:191], v[122:125]
	v_mfma_f32_16x16x32_bf16 v[110:113], v[156:159], v[200:203], v[110:113]
	v_mfma_f32_16x16x32_bf16 v[106:109], v[164:167], v[200:203], v[106:109]
	v_mfma_f32_16x16x32_bf16 v[94:97], v[156:159], v[208:211], v[94:97]
	v_mfma_f32_16x16x32_bf16 v[90:93], v[164:167], v[208:211], v[90:93]
	v_mfma_f32_16x16x32_bf16 v[78:81], v[156:159], v[216:219], v[78:81]
	v_mfma_f32_16x16x32_bf16 v[74:77], v[164:167], v[216:219], v[74:77]
	v_mfma_f32_16x16x32_bf16 v[118:121], v[168:171], v[184:187], v[118:121]
	v_mfma_f32_16x16x32_bf16 v[114:117], v[176:179], v[184:187], v[114:117]
	v_mfma_f32_16x16x32_bf16 v[102:105], v[168:171], v[196:199], v[102:105]
	v_mfma_f32_16x16x32_bf16 v[98:101], v[176:179], v[196:199], v[98:101]
	v_mfma_f32_16x16x32_bf16 v[86:89], v[168:171], v[204:207], v[86:89]
	v_mfma_f32_16x16x32_bf16 v[82:85], v[176:179], v[204:207], v[82:85]
	v_mfma_f32_16x16x32_bf16 v[70:73], v[168:171], v[212:215], v[70:73]
	v_mfma_f32_16x16x32_bf16 v[66:69], v[176:179], v[212:215], v[66:69]
	v_mfma_f32_16x16x32_bf16 v[118:121], v[172:175], v[188:191], v[118:121]
	v_mfma_f32_16x16x32_bf16 v[114:117], v[180:183], v[188:191], v[114:117]
	v_mfma_f32_16x16x32_bf16 v[102:105], v[172:175], v[200:203], v[102:105]
	v_mfma_f32_16x16x32_bf16 v[98:101], v[180:183], v[200:203], v[98:101]
	v_mfma_f32_16x16x32_bf16 v[86:89], v[172:175], v[208:211], v[86:89]
	v_mfma_f32_16x16x32_bf16 v[82:85], v[180:183], v[208:211], v[82:85]
	v_mfma_f32_16x16x32_bf16 v[70:73], v[172:175], v[216:219], v[70:73]
	v_mfma_f32_16x16x32_bf16 v[66:69], v[180:183], v[216:219], v[66:69]
	s_barrier
	s_add_i32 m0, s38, 0x10000
	ds_read_b128 v[184:187], v154 offset:16384
	ds_read_b128 v[188:191], v154 offset:17408
	ds_read_b128 v[196:199], v154 offset:18432
	ds_read_b128 v[200:203], v154 offset:19456
	ds_read_b128 v[204:207], v154 offset:20480
	ds_read_b128 v[208:211], v154 offset:21504
	ds_read_b128 v[212:215], v154 offset:22528
	ds_read_b128 v[216:219], v154 offset:23552
	global_load_lds_dwordx4 v132, s[34:35]
	s_add_i32 m0, s38, 0x12000
	s_add_u32 s56, s34, 0x80000
	s_addc_u32 s57, s35, 0
	global_load_lds_dwordx4 v136, s[34:35]
	s_add_i32 m0, s38, 0x14000
	s_nop 0
	global_load_lds_dwordx4 v132, s[56:57]
	s_add_i32 m0, s38, 0x16000
	s_nop 0
	global_load_lds_dwordx4 v136, s[56:57]
	s_mov_b32 m0, s27
	s_nop 0
	global_load_lds_dwordx4 v130, s[36:37]
	s_mov_b32 m0, s29
	s_nop 0
	global_load_lds_dwordx4 v134, s[36:37]
	s_waitcnt vmcnt(8) lgkmcnt(0)
	s_barrier
	v_mfma_f32_16x16x32_bf16 v[62:65], v[144:147], v[184:187], v[62:65]
	v_mfma_f32_16x16x32_bf16 v[58:61], v[160:163], v[184:187], v[58:61]
	v_mfma_f32_16x16x32_bf16 v[46:49], v[144:147], v[196:199], v[46:49]
	v_mfma_f32_16x16x32_bf16 v[42:45], v[160:163], v[196:199], v[42:45]
	v_mfma_f32_16x16x32_bf16 v[30:33], v[144:147], v[204:207], v[30:33]
	v_mfma_f32_16x16x32_bf16 v[26:29], v[160:163], v[204:207], v[26:29]
	v_mfma_f32_16x16x32_bf16 v[14:17], v[144:147], v[212:215], v[14:17]
	v_mfma_f32_16x16x32_bf16 v[10:13], v[160:163], v[212:215], v[10:13]
	v_mfma_f32_16x16x32_bf16 v[62:65], v[156:159], v[188:191], v[62:65]
	v_mfma_f32_16x16x32_bf16 v[58:61], v[164:167], v[188:191], v[58:61]
	v_mfma_f32_16x16x32_bf16 v[46:49], v[156:159], v[200:203], v[46:49]
	v_mfma_f32_16x16x32_bf16 v[42:45], v[164:167], v[200:203], v[42:45]
	v_mfma_f32_16x16x32_bf16 v[30:33], v[156:159], v[208:211], v[30:33]
	v_mfma_f32_16x16x32_bf16 v[26:29], v[164:167], v[208:211], v[26:29]
	v_mfma_f32_16x16x32_bf16 v[14:17], v[156:159], v[216:219], v[14:17]
	v_mfma_f32_16x16x32_bf16 v[10:13], v[164:167], v[216:219], v[10:13]
	v_mfma_f32_16x16x32_bf16 v[54:57], v[168:171], v[184:187], v[54:57]
	v_mfma_f32_16x16x32_bf16 v[50:53], v[176:179], v[184:187], v[50:53]
	v_mfma_f32_16x16x32_bf16 v[38:41], v[168:171], v[196:199], v[38:41]
	v_mfma_f32_16x16x32_bf16 v[34:37], v[176:179], v[196:199], v[34:37]
	v_mfma_f32_16x16x32_bf16 v[22:25], v[168:171], v[204:207], v[22:25]
	v_mfma_f32_16x16x32_bf16 v[18:21], v[176:179], v[204:207], v[18:21]
	v_mfma_f32_16x16x32_bf16 v[6:9], v[168:171], v[212:215], v[6:9]
	v_mfma_f32_16x16x32_bf16 v[2:5], v[176:179], v[212:215], v[2:5]
	v_mfma_f32_16x16x32_bf16 v[54:57], v[172:175], v[188:191], v[54:57]
	v_mfma_f32_16x16x32_bf16 v[50:53], v[180:183], v[188:191], v[50:53]
	v_mfma_f32_16x16x32_bf16 v[38:41], v[172:175], v[200:203], v[38:41]
	v_mfma_f32_16x16x32_bf16 v[34:37], v[180:183], v[200:203], v[34:37]
	v_mfma_f32_16x16x32_bf16 v[22:25], v[172:175], v[208:211], v[22:25]
	v_mfma_f32_16x16x32_bf16 v[18:21], v[180:183], v[208:211], v[18:21]
	v_mfma_f32_16x16x32_bf16 v[6:9], v[172:175], v[216:219], v[6:9]
	v_mfma_f32_16x16x32_bf16 v[2:5], v[180:183], v[216:219], v[2:5]
	s_barrier
	ds_read_b128 v[144:147], v148
	ds_read_b128 v[156:159], v148 offset:1024
	ds_read_b128 v[160:163], v148 offset:2048
	ds_read_b128 v[164:167], v148 offset:3072
	ds_read_b128 v[168:171], v149
	ds_read_b128 v[172:175], v149 offset:1024
	ds_read_b128 v[176:179], v149 offset:2048
	ds_read_b128 v[180:183], v149 offset:3072
	s_add_u32 s36, s36, 0x80000
	s_addc_u32 s37, s37, 0
	s_mov_b32 m0, s39
	ds_read_b128 v[184:187], v154 offset:32768
	ds_read_b128 v[188:191], v154 offset:33792
	ds_read_b128 v[196:199], v154 offset:34816
	ds_read_b128 v[200:203], v154 offset:35840
	ds_read_b128 v[204:207], v154 offset:36864
	ds_read_b128 v[208:211], v154 offset:37888
	ds_read_b128 v[212:215], v154 offset:38912
	ds_read_b128 v[216:219], v154 offset:39936
	global_load_lds_dwordx4 v130, s[36:37]
	s_mov_b32 m0, s40
	s_nop 0
	global_load_lds_dwordx4 v134, s[36:37]
	s_waitcnt vmcnt(8) lgkmcnt(0)
	s_barrier
	v_mfma_f32_16x16x32_bf16 v[126:129], v[144:147], v[184:187], v[126:129]
	v_mfma_f32_16x16x32_bf16 v[122:125], v[160:163], v[184:187], v[122:125]
	v_mfma_f32_16x16x32_bf16 v[110:113], v[144:147], v[196:199], v[110:113]
	v_mfma_f32_16x16x32_bf16 v[106:109], v[160:163], v[196:199], v[106:109]
	v_mfma_f32_16x16x32_bf16 v[94:97], v[144:147], v[204:207], v[94:97]
	v_mfma_f32_16x16x32_bf16 v[90:93], v[160:163], v[204:207], v[90:93]
	v_mfma_f32_16x16x32_bf16 v[78:81], v[144:147], v[212:215], v[78:81]
	v_mfma_f32_16x16x32_bf16 v[74:77], v[160:163], v[212:215], v[74:77]
	v_mfma_f32_16x16x32_bf16 v[126:129], v[156:159], v[188:191], v[126:129]
	v_mfma_f32_16x16x32_bf16 v[122:125], v[164:167], v[188:191], v[122:125]
	v_mfma_f32_16x16x32_bf16 v[110:113], v[156:159], v[200:203], v[110:113]
	v_mfma_f32_16x16x32_bf16 v[106:109], v[164:167], v[200:203], v[106:109]
	v_mfma_f32_16x16x32_bf16 v[94:97], v[156:159], v[208:211], v[94:97]
	v_mfma_f32_16x16x32_bf16 v[90:93], v[164:167], v[208:211], v[90:93]
	v_mfma_f32_16x16x32_bf16 v[78:81], v[156:159], v[216:219], v[78:81]
	v_mfma_f32_16x16x32_bf16 v[74:77], v[164:167], v[216:219], v[74:77]
	v_mfma_f32_16x16x32_bf16 v[118:121], v[168:171], v[184:187], v[118:121]
	v_mfma_f32_16x16x32_bf16 v[114:117], v[176:179], v[184:187], v[114:117]
	v_mfma_f32_16x16x32_bf16 v[102:105], v[168:171], v[196:199], v[102:105]
	v_mfma_f32_16x16x32_bf16 v[98:101], v[176:179], v[196:199], v[98:101]
	v_mfma_f32_16x16x32_bf16 v[86:89], v[168:171], v[204:207], v[86:89]
	v_mfma_f32_16x16x32_bf16 v[82:85], v[176:179], v[204:207], v[82:85]
	v_mfma_f32_16x16x32_bf16 v[70:73], v[168:171], v[212:215], v[70:73]
	v_mfma_f32_16x16x32_bf16 v[66:69], v[176:179], v[212:215], v[66:69]
	v_mfma_f32_16x16x32_bf16 v[118:121], v[172:175], v[188:191], v[118:121]
	v_mfma_f32_16x16x32_bf16 v[114:117], v[180:183], v[188:191], v[114:117]
	v_mfma_f32_16x16x32_bf16 v[102:105], v[172:175], v[200:203], v[102:105]
	v_mfma_f32_16x16x32_bf16 v[98:101], v[180:183], v[200:203], v[98:101]
	v_mfma_f32_16x16x32_bf16 v[86:89], v[172:175], v[208:211], v[86:89]
	v_mfma_f32_16x16x32_bf16 v[82:85], v[180:183], v[208:211], v[82:85]
	v_mfma_f32_16x16x32_bf16 v[70:73], v[172:175], v[216:219], v[70:73]
	v_mfma_f32_16x16x32_bf16 v[66:69], v[180:183], v[216:219], v[66:69]
	s_barrier
	s_add_u32 s98, s36, 0xfff80080
	s_addc_u32 s99, s37, -1
	s_add_i32 m0, s38, 0x18000
	ds_read_b128 v[184:187], v154 offset:49152
	ds_read_b128 v[188:191], v154 offset:50176
	ds_read_b128 v[196:199], v154 offset:51200
	ds_read_b128 v[200:203], v154 offset:52224
	ds_read_b128 v[204:207], v154 offset:53248
	ds_read_b128 v[208:211], v154 offset:54272
	ds_read_b128 v[212:215], v154 offset:55296
	ds_read_b128 v[216:219], v154 offset:56320
	s_add_u32 s100, s34, 0x80
	s_addc_u32 s101, s35, 0
	global_load_lds_dwordx4 v132, s[100:101]
	s_add_i32 m0, s38, 0x1a000
	s_add_u32 s34, s34, 0x80080
	s_addc_u32 s35, s35, 0
	global_load_lds_dwordx4 v136, s[100:101]
	s_add_i32 m0, s38, 0x1c000
	s_nop 0
	global_load_lds_dwordx4 v132, s[34:35]
	s_add_i32 m0, s38, 0x1e000
	s_nop 0
	global_load_lds_dwordx4 v136, s[34:35]
	s_mov_b32 m0, s42
	s_nop 0
	global_load_lds_dwordx4 v130, s[98:99]
	s_mov_b32 m0, s43
	s_nop 0
	global_load_lds_dwordx4 v134, s[98:99]
	s_waitcnt vmcnt(8) lgkmcnt(0)
	s_barrier
	v_mfma_f32_16x16x32_bf16 v[62:65], v[144:147], v[184:187], v[62:65]
	v_mfma_f32_16x16x32_bf16 v[58:61], v[160:163], v[184:187], v[58:61]
	v_mfma_f32_16x16x32_bf16 v[46:49], v[144:147], v[196:199], v[46:49]
	v_mfma_f32_16x16x32_bf16 v[42:45], v[160:163], v[196:199], v[42:45]
	v_mfma_f32_16x16x32_bf16 v[30:33], v[144:147], v[204:207], v[30:33]
	v_mfma_f32_16x16x32_bf16 v[26:29], v[160:163], v[204:207], v[26:29]
	v_mfma_f32_16x16x32_bf16 v[14:17], v[144:147], v[212:215], v[14:17]
	v_mfma_f32_16x16x32_bf16 v[10:13], v[160:163], v[212:215], v[10:13]
	v_mfma_f32_16x16x32_bf16 v[62:65], v[156:159], v[188:191], v[62:65]
	v_mfma_f32_16x16x32_bf16 v[58:61], v[164:167], v[188:191], v[58:61]
	v_mfma_f32_16x16x32_bf16 v[46:49], v[156:159], v[200:203], v[46:49]
	v_mfma_f32_16x16x32_bf16 v[42:45], v[164:167], v[200:203], v[42:45]
	v_mfma_f32_16x16x32_bf16 v[30:33], v[156:159], v[208:211], v[30:33]
	v_mfma_f32_16x16x32_bf16 v[26:29], v[164:167], v[208:211], v[26:29]
	v_mfma_f32_16x16x32_bf16 v[14:17], v[156:159], v[216:219], v[14:17]
	v_mfma_f32_16x16x32_bf16 v[10:13], v[164:167], v[216:219], v[10:13]
	v_mfma_f32_16x16x32_bf16 v[54:57], v[168:171], v[184:187], v[54:57]
	v_mfma_f32_16x16x32_bf16 v[50:53], v[176:179], v[184:187], v[50:53]
	v_mfma_f32_16x16x32_bf16 v[38:41], v[168:171], v[196:199], v[38:41]
	v_mfma_f32_16x16x32_bf16 v[34:37], v[176:179], v[196:199], v[34:37]
	v_mfma_f32_16x16x32_bf16 v[22:25], v[168:171], v[204:207], v[22:25]
	v_mfma_f32_16x16x32_bf16 v[18:21], v[176:179], v[204:207], v[18:21]
	v_mfma_f32_16x16x32_bf16 v[6:9], v[168:171], v[212:215], v[6:9]
	v_mfma_f32_16x16x32_bf16 v[2:5], v[176:179], v[212:215], v[2:5]
	v_mfma_f32_16x16x32_bf16 v[54:57], v[172:175], v[188:191], v[54:57]
	v_mfma_f32_16x16x32_bf16 v[50:53], v[180:183], v[188:191], v[50:53]
	v_mfma_f32_16x16x32_bf16 v[38:41], v[172:175], v[200:203], v[38:41]
	v_mfma_f32_16x16x32_bf16 v[34:37], v[180:183], v[200:203], v[34:37]
	v_mfma_f32_16x16x32_bf16 v[22:25], v[172:175], v[208:211], v[22:25]
	v_mfma_f32_16x16x32_bf16 v[18:21], v[180:183], v[208:211], v[18:21]
	v_mfma_f32_16x16x32_bf16 v[6:9], v[172:175], v[216:219], v[6:9]
	v_mfma_f32_16x16x32_bf16 v[2:5], v[180:183], v[216:219], v[2:5]
	s_barrier
	s_add_i32 s55, s55, 2
	s_add_u32 s53, s53, 0x100
	s_addc_u32 s54, s54, 0
	s_add_u32 s30, s30, 0x100
	s_addc_u32 s31, s31, 0
	s_cmp_gt_u32 s55, 29
	s_cbranch_scc0 .LBB0_808
	s_setprio 0
	s_and_b64 vcc, exec, s[12:13]
	s_cbranch_vccz .LBB0_811
	s_barrier

.LBB0_1030:
	v_and_b32_e32 v1, 15, v0
	v_and_b32_e32 v14, 48, v0
	v_lshlrev_b32_e32 v16, 2, v0
	s_lshl_b32 s24, s4, 6
	v_lshl_or_b32 v15, v1, 6, v14
	s_lshl_b32 s4, s4, 13
	v_and_b32_e32 v16, 32, v16
	s_and_b32 s18, s17, 3
	v_bitop3_b32 v15, v15, s4, v16 bitop3:0xde
	v_lshlrev_b32_e32 v17, 6, v0
	s_movk_i32 s4, 0x3c0
	v_and_or_b32 v14, v17, s4, v14
	s_lshl_b32 s4, s18, 12
	v_bitop3_b32 v14, s4, v14, v16 bitop3:0xf6
	s_mov_b64 s[4:5], 0x80
	s_add_i32 m0, s20, 0x18000
	v_lshl_add_u64 v[8:9], v[8:9], 0, s[4:5]
	s_waitcnt vmcnt(2)
	s_barrier
	global_load_lds_dwordx4 v[8:9], off
	v_lshl_add_u64 v[6:7], v[6:7], 0, s[4:5]
	s_add_i32 m0, s20, 0x1a000
	s_add_i32 s25, s20, 0x8000
	s_add_i32 s26, s20, 0xa000
	global_load_lds_dwordx4 v[6:7], off
	v_lshl_add_u64 v[4:5], v[4:5], 0, s[4:5]
	s_mov_b32 m0, s25
	s_add_u32 s8, s0, 0x200080
	global_load_lds_dwordx4 v[4:5], off
	v_lshl_add_u64 v[2:3], v[2:3], 0, s[4:5]
	s_mov_b32 m0, s26
	s_addc_u32 s9, s1, 0
	global_load_lds_dwordx4 v[2:3], off
	s_add_i32 m0, s20, 0x1c000
	v_lshl_add_u64 v[2:3], s[8:9], 0, v[130:131]
	global_load_lds_dwordx4 v[2:3], off
	v_lshl_add_u64 v[2:3], s[8:9], 0, v[132:133]
	s_add_i32 m0, s20, 0x1e000
	s_add_u32 s8, s70, s13
	global_load_lds_dwordx4 v[2:3], off
	s_addc_u32 s9, s71, 0
	s_add_u32 s27, s8, 0xc000100
	v_lshlrev_b32_e32 v2, 11, v0
	s_addc_u32 s28, s9, 0
	v_and_b32_e32 v2, 0xc0000, v2
	v_lshlrev_b32_e32 v4, 14, v13
	s_add_u32 s8, s70, s10
	v_or3_b32 v2, v10, v2, v4
	s_addc_u32 s9, s71, s11
	v_add_u32_e32 v2, v2, v11
	v_mov_b32_e32 v3, v131
	v_lshl_add_u64 v[2:3], s[8:9], 0, v[2:3]
	s_mov_b64 s[10:11], 0x2200080
	v_lshl_add_u64 v[134:135], v[2:3], 0, s[10:11]
	v_lshlrev_b32_e32 v2, 7, v12
	v_and_b32_e32 v2, 0x1c0000, v2
	v_or3_b32 v2, v10, v2, v4
	s_waitcnt vmcnt(6)
	v_add_u32_e32 v2, v2, v11
	v_mov_b32_e32 v3, v131
	s_add_i32 s34, 0, 0x10000
	s_add_i32 s36, 0, 0x14000
	s_add_i32 s38, 0, 0x18000
	s_add_i32 s40, 0, 0x1c000
	v_lshl_add_u64 v[2:3], s[8:9], 0, v[2:3]
	v_add_u32_e32 v139, s34, v14
	v_add_u32_e32 v140, s36, v14
	s_add_i32 s34, s34, s12
	s_add_i32 s36, s36, s12
	v_add_u32_e32 v142, s38, v14
	v_add_u32_e32 v143, s40, v14
	s_add_i32 s38, s38, s12
	s_add_i32 s40, s40, s12
	v_readlane_b32 s44, v242, 16
	v_lshrrev_b32_e32 v138, 2, v0
	v_or_b32_e32 v162, s24, v1
	v_lshl_add_u64 v[136:137], v[2:3], 0, s[10:11]
	s_mov_b32 s29, -2
	s_mov_b64 s[10:11], 0
	v_add_u32_e32 v141, 0, v15
	s_add_i32 s30, s20, 0xc000
	s_add_i32 s31, s20, 0xe000
	s_add_i32 s35, s34, 0x2000
	s_add_i32 s37, s36, 0x2000
	s_add_i32 s39, s38, 0x2000
	s_add_i32 s41, s40, 0x2000
	v_mov_b32_e32 v2, v131
	v_mov_b32_e32 v3, v131
	v_mov_b32_e32 v4, v131
	v_mov_b32_e32 v5, v131
	v_mov_b32_e32 v6, v131
	v_mov_b32_e32 v7, v131
	v_mov_b32_e32 v8, v131
	v_mov_b32_e32 v9, v131
	v_mov_b32_e32 v18, v131
	v_mov_b32_e32 v19, v131
	v_mov_b32_e32 v20, v131
	v_mov_b32_e32 v21, v131
	v_mov_b32_e32 v22, v131
	v_mov_b32_e32 v23, v131
	v_mov_b32_e32 v24, v131
	v_mov_b32_e32 v25, v131
	v_mov_b32_e32 v34, v131
	v_mov_b32_e32 v35, v131
	v_mov_b32_e32 v36, v131
	v_mov_b32_e32 v37, v131
	v_mov_b32_e32 v38, v131
	v_mov_b32_e32 v39, v131
	v_mov_b32_e32 v40, v131
	v_mov_b32_e32 v41, v131
	v_mov_b32_e32 v50, v131
	v_mov_b32_e32 v51, v131
	v_mov_b32_e32 v52, v131
	v_mov_b32_e32 v53, v131
	v_mov_b32_e32 v54, v131
	v_mov_b32_e32 v55, v131
	v_mov_b32_e32 v56, v131
	v_mov_b32_e32 v57, v131
	v_mov_b32_e32 v10, v131
	v_mov_b32_e32 v11, v131
	v_mov_b32_e32 v12, v131
	v_mov_b32_e32 v13, v131
	v_mov_b32_e32 v14, v131
	v_mov_b32_e32 v15, v131
	v_mov_b32_e32 v16, v131
	v_mov_b32_e32 v17, v131
	v_mov_b32_e32 v26, v131
	v_mov_b32_e32 v27, v131
	v_mov_b32_e32 v28, v131
	v_mov_b32_e32 v29, v131
	v_mov_b32_e32 v30, v131
	v_mov_b32_e32 v31, v131
	v_mov_b32_e32 v32, v131
	v_mov_b32_e32 v33, v131
	v_mov_b32_e32 v42, v131
	v_mov_b32_e32 v43, v131
	v_mov_b32_e32 v44, v131
	v_mov_b32_e32 v45, v131
	v_mov_b32_e32 v46, v131
	v_mov_b32_e32 v47, v131
	v_mov_b32_e32 v48, v131
	v_mov_b32_e32 v49, v131
	v_mov_b32_e32 v58, v131
	v_mov_b32_e32 v59, v131
	v_mov_b32_e32 v60, v131
	v_mov_b32_e32 v61, v131
	v_mov_b32_e32 v62, v131
	v_mov_b32_e32 v63, v131
	v_mov_b32_e32 v64, v131
	v_mov_b32_e32 v65, v131
	v_mov_b32_e32 v66, v131
	v_mov_b32_e32 v67, v131
	v_mov_b32_e32 v68, v131
	v_mov_b32_e32 v69, v131
	v_mov_b32_e32 v70, v131
	v_mov_b32_e32 v71, v131
	v_mov_b32_e32 v72, v131
	v_mov_b32_e32 v73, v131
	v_mov_b32_e32 v82, v131
	v_mov_b32_e32 v83, v131
	v_mov_b32_e32 v84, v131
	v_mov_b32_e32 v85, v131
	v_mov_b32_e32 v86, v131
	v_mov_b32_e32 v87, v131
	v_mov_b32_e32 v88, v131
	v_mov_b32_e32 v89, v131
	v_mov_b32_e32 v98, v131
	v_mov_b32_e32 v99, v131
	v_mov_b32_e32 v100, v131
	v_mov_b32_e32 v101, v131
	v_mov_b32_e32 v102, v131
	v_mov_b32_e32 v103, v131
	v_mov_b32_e32 v104, v131
	v_mov_b32_e32 v105, v131
	v_mov_b32_e32 v114, v131
	v_mov_b32_e32 v115, v131
	v_mov_b32_e32 v116, v131
	v_mov_b32_e32 v117, v131
	v_mov_b32_e32 v118, v131
	v_mov_b32_e32 v119, v131
	v_mov_b32_e32 v120, v131
	v_mov_b32_e32 v121, v131
	v_mov_b32_e32 v74, v131
	v_mov_b32_e32 v75, v131
	v_mov_b32_e32 v76, v131
	v_mov_b32_e32 v77, v131
	v_mov_b32_e32 v78, v131
	v_mov_b32_e32 v79, v131
	v_mov_b32_e32 v80, v131
	v_mov_b32_e32 v81, v131
	v_mov_b32_e32 v90, v131
	v_mov_b32_e32 v91, v131
	v_mov_b32_e32 v92, v131
	v_mov_b32_e32 v93, v131
	v_mov_b32_e32 v94, v131
	v_mov_b32_e32 v95, v131
	v_mov_b32_e32 v96, v131
	v_mov_b32_e32 v97, v131
	v_mov_b32_e32 v106, v131
	v_mov_b32_e32 v107, v131
	v_mov_b32_e32 v108, v131
	v_mov_b32_e32 v109, v131
	v_mov_b32_e32 v110, v131
	v_mov_b32_e32 v111, v131
	v_mov_b32_e32 v112, v131
	v_mov_b32_e32 v113, v131
	v_mov_b32_e32 v122, v131
	v_mov_b32_e32 v123, v131
	v_mov_b32_e32 v124, v131
	v_mov_b32_e32 v125, v131
	v_mov_b32_e32 v126, v131
	v_mov_b32_e32 v127, v131
	v_mov_b32_e32 v128, v131
	v_mov_b32_e32 v129, v131
	v_readlane_b32 s45, v242, 17
	s_barrier
	s_cmpk_gt_u32 s19, 0xff
	s_cbranch_scc0 .Lhp_skip_5
	s_setprio 1
; __device__ __forceinline__ f32x4 bf4_to_f32(u32x2 w) { f32x4 r; r[0] = __uint_as_float(w.x << 16); r[1] = __uint_as_float(w.x & 0xffff0000u); r[2] = __uint_as_float(w.y << 16); r[3] = __uint_as_float(w.y & 0xffff0000u); return r; }
;     __device__ __forceinline__ void fused(f32x4 (&acc)[2][2][4][2], const Unit& u, int wr, int wc, int fr, int fq, PG8_LAS unsigned char* lds, int wid, int lane) const {
;     ...
;             for (int m = 0; m < 4; ++m) { const int r = ai * HALF + wr * 64 + m * 16 + fr; const size_t off = (size_t)(u.pm * BM + r) * 2048 + col0; float s = 0.f;
;                 const float rr = __builtin_amdgcn_rcpf(r2[ai * 4 + m] * (1.0f / 2048.0f) + 1e-5f);
; #pragma unroll
;                 for (int bj = 0; bj < 2; ++bj)
; #pragma unroll
;                     for (int n = 0; n < 2; ++n) { const f32x4 bs = bf4_to_f32(*(const u32x2*)(base + off + bj * HALF + n * 16)); const f32x4 o = bs + acc[ai][bj][m][n] * rr; acc[ai][bj][m][n] = o;
.Lhp_skip_5:
.LBB0_1031:
	s_cmpk_eq_i32 s29, 118
	s_cbranch_scc0 .Lp5pf_skip
	s_lshl_b32 s46, s64, 8
	s_lshl_b32 s47, s18, 5
	s_lshl_b32 s48, s16, 8
	s_or_b32 s48, s48, s47
	v_add_u32_e32 v216, s46, v162
	v_ashrrev_i32_e32 v217, 31, v216
	v_lshlrev_b64 v[216:217], 12, v[216:217]
	v_lshl_add_u64 v[216:217], s[70:71], 0, v[216:217]
	v_and_or_b32 v192, v138, 12, s48
	v_lshlrev_b32_e32 v192, 1, v192
	v_mov_b32_e32 v193, 0
	v_lshl_add_u64 v[216:217], v[216:217], 0, v[192:193]
	s_mov_b64 s[46:47], 0x10000
	v_lshl_add_u64 v[192:193], v[216:217], 0, s[46:47]
	global_load_dwordx2 v[218:219], v[192:193], off
	global_load_dwordx2 v[220:221], v[192:193], off offset:32
	global_load_dwordx2 v[222:223], v[192:193], off offset:256
	global_load_dwordx2 v[224:225], v[192:193], off offset:288
	s_mov_b64 s[46:47], 0x20000
	v_lshl_add_u64 v[192:193], v[216:217], 0, s[46:47]
	global_load_dwordx2 v[226:227], v[192:193], off
	global_load_dwordx2 v[228:229], v[192:193], off offset:32
	global_load_dwordx2 v[230:231], v[192:193], off offset:256
	global_load_dwordx2 v[232:233], v[192:193], off offset:288
	s_mov_b64 s[46:47], 0x30000
	v_lshl_add_u64 v[192:193], v[216:217], 0, s[46:47]
	global_load_dwordx2 v[234:235], v[192:193], off
	global_load_dwordx2 v[236:237], v[192:193], off offset:32
	global_load_dwordx2 v[238:239], v[192:193], off offset:256
	global_load_dwordx2 v[240:241], v[192:193], off offset:288
	s_mov_b64 s[46:47], 0x80000
	v_lshl_add_u64 v[192:193], v[216:217], 0, s[46:47]
	global_load_dwordx2 v[244:245], v[192:193], off
	global_load_dwordx2 v[246:247], v[192:193], off offset:32
	global_load_dwordx2 v[248:249], v[192:193], off offset:256
	global_load_dwordx2 v[250:251], v[192:193], off offset:288
	s_mov_b64 s[46:47], 0x90000
	v_lshl_add_u64 v[192:193], v[216:217], 0, s[46:47]
	global_load_dwordx2 v[252:253], v[192:193], off
	global_load_dwordx2 v[254:255], v[192:193], off offset:32
	global_load_dwordx2 v[216:217], v[192:193], off offset:256
	s_nop 0
	global_load_dwordx2 v[192:193], v[192:193], off offset:288
.Lp5pf_skip:
	ds_read_b128 v[144:147], v139
	ds_read_b128 v[148:151], v139 offset:1024
	ds_read_b128 v[152:155], v139 offset:2048
	ds_read_b128 v[156:159], v139 offset:3072
	ds_read_b128 v[164:167], v140
	ds_read_b128 v[168:171], v140 offset:1024
	ds_read_b128 v[172:175], v140 offset:2048
	ds_read_b128 v[176:179], v140 offset:3072
	s_add_u32 s12, s8, s10
	s_addc_u32 s13, s9, s11
	s_add_u32 s12, s12, 0x2000100
	s_addc_u32 s13, s13, 0
	s_add_u32 s42, s27, s10
	s_addc_u32 s43, s28, s11
	s_cmpk_eq_i32 s10, 0x3f00
	s_cselect_b32 s15, s3, s13
	s_cselect_b32 s14, s2, s12
	s_cselect_b32 s13, s1, s43
	s_cselect_b32 s12, s0, s42
	s_mov_b32 m0, s30
	v_lshl_add_u64 v[160:161], v[134:135], 0, s[10:11]
	ds_read_b128 v[180:183], v141
	ds_read_b128 v[184:187], v141 offset:1024
	ds_read_b128 v[188:191], v141 offset:2048
	ds_read_b128 v[196:199], v141 offset:3072
	ds_read_b128 v[200:203], v141 offset:4096
	ds_read_b128 v[204:207], v141 offset:5120
	ds_read_b128 v[208:211], v141 offset:6144
	ds_read_b128 v[212:215], v141 offset:7168
	global_load_lds_dwordx4 v[160:161], off
	v_lshl_add_u64 v[160:161], v[136:137], 0, s[10:11]
	s_mov_b32 m0, s31
	s_nop 0
	global_load_lds_dwordx4 v[160:161], off
	s_waitcnt vmcnt(8) lgkmcnt(0)
	s_barrier
	v_mfma_f32_16x16x32_bf16 v[126:129], v[144:147], v[180:183], v[126:129]
	v_mfma_f32_16x16x32_bf16 v[122:125], v[152:155], v[180:183], v[122:125]
	v_mfma_f32_16x16x32_bf16 v[110:113], v[144:147], v[188:191], v[110:113]
	v_mfma_f32_16x16x32_bf16 v[106:109], v[152:155], v[188:191], v[106:109]
	v_mfma_f32_16x16x32_bf16 v[94:97], v[144:147], v[200:203], v[94:97]
	v_mfma_f32_16x16x32_bf16 v[90:93], v[152:155], v[200:203], v[90:93]
	v_mfma_f32_16x16x32_bf16 v[78:81], v[144:147], v[208:211], v[78:81]
	v_mfma_f32_16x16x32_bf16 v[74:77], v[152:155], v[208:211], v[74:77]
	v_mfma_f32_16x16x32_bf16 v[126:129], v[148:151], v[184:187], v[126:129]
	v_mfma_f32_16x16x32_bf16 v[122:125], v[156:159], v[184:187], v[122:125]
	v_mfma_f32_16x16x32_bf16 v[110:113], v[148:151], v[196:199], v[110:113]
	v_mfma_f32_16x16x32_bf16 v[106:109], v[156:159], v[196:199], v[106:109]
	v_mfma_f32_16x16x32_bf16 v[94:97], v[148:151], v[204:207], v[94:97]
	v_mfma_f32_16x16x32_bf16 v[90:93], v[156:159], v[204:207], v[90:93]
	v_mfma_f32_16x16x32_bf16 v[78:81], v[148:151], v[212:215], v[78:81]
	v_mfma_f32_16x16x32_bf16 v[74:77], v[156:159], v[212:215], v[74:77]
	v_mfma_f32_16x16x32_bf16 v[118:121], v[164:167], v[180:183], v[118:121]
	v_mfma_f32_16x16x32_bf16 v[114:117], v[172:175], v[180:183], v[114:117]
	v_mfma_f32_16x16x32_bf16 v[102:105], v[164:167], v[188:191], v[102:105]
	v_mfma_f32_16x16x32_bf16 v[98:101], v[172:175], v[188:191], v[98:101]
	v_mfma_f32_16x16x32_bf16 v[86:89], v[164:167], v[200:203], v[86:89]
	v_mfma_f32_16x16x32_bf16 v[82:85], v[172:175], v[200:203], v[82:85]
	v_mfma_f32_16x16x32_bf16 v[70:73], v[164:167], v[208:211], v[70:73]
	v_mfma_f32_16x16x32_bf16 v[66:69], v[172:175], v[208:211], v[66:69]
	v_mfma_f32_16x16x32_bf16 v[118:121], v[168:171], v[184:187], v[118:121]
	v_mfma_f32_16x16x32_bf16 v[114:117], v[176:179], v[184:187], v[114:117]
	v_mfma_f32_16x16x32_bf16 v[102:105], v[168:171], v[196:199], v[102:105]
	v_mfma_f32_16x16x32_bf16 v[98:101], v[176:179], v[196:199], v[98:101]
	v_mfma_f32_16x16x32_bf16 v[86:89], v[168:171], v[204:207], v[86:89]
	v_mfma_f32_16x16x32_bf16 v[82:85], v[176:179], v[204:207], v[82:85]
	v_mfma_f32_16x16x32_bf16 v[70:73], v[168:171], v[212:215], v[70:73]
	v_mfma_f32_16x16x32_bf16 v[66:69], v[176:179], v[212:215], v[66:69]
	s_barrier
	s_mov_b32 m0, s34
	s_add_u32 s42, s12, 0x200000
	s_addc_u32 s43, s13, 0
	ds_read_b128 v[180:183], v141 offset:16384
	ds_read_b128 v[184:187], v141 offset:17408
	ds_read_b128 v[188:191], v141 offset:18432
	ds_read_b128 v[196:199], v141 offset:19456
	ds_read_b128 v[200:203], v141 offset:20480
	ds_read_b128 v[204:207], v141 offset:21504
	ds_read_b128 v[208:211], v141 offset:22528
	ds_read_b128 v[212:215], v141 offset:23552
	global_load_lds_dwordx4 v130, s[12:13]
	s_mov_b32 m0, s35
	s_nop 0
	global_load_lds_dwordx4 v132, s[12:13]
	s_mov_b32 m0, s36
	s_nop 0
	global_load_lds_dwordx4 v130, s[42:43]
	s_mov_b32 m0, s37
	s_nop 0
	global_load_lds_dwordx4 v132, s[42:43]
	s_mov_b32 m0, s20
	s_nop 0
	global_load_lds_dwordx4 v130, s[14:15]
	s_mov_b32 m0, s21
	s_nop 0
	global_load_lds_dwordx4 v132, s[14:15]
	s_waitcnt vmcnt(8) lgkmcnt(0)
	s_barrier
	v_mfma_f32_16x16x32_bf16 v[62:65], v[144:147], v[180:183], v[62:65]
	v_mfma_f32_16x16x32_bf16 v[58:61], v[152:155], v[180:183], v[58:61]
	v_mfma_f32_16x16x32_bf16 v[46:49], v[144:147], v[188:191], v[46:49]
	v_mfma_f32_16x16x32_bf16 v[42:45], v[152:155], v[188:191], v[42:45]
	v_mfma_f32_16x16x32_bf16 v[30:33], v[144:147], v[200:203], v[30:33]
	v_mfma_f32_16x16x32_bf16 v[26:29], v[152:155], v[200:203], v[26:29]
	v_mfma_f32_16x16x32_bf16 v[14:17], v[144:147], v[208:211], v[14:17]
	v_mfma_f32_16x16x32_bf16 v[10:13], v[152:155], v[208:211], v[10:13]
	v_mfma_f32_16x16x32_bf16 v[62:65], v[148:151], v[184:187], v[62:65]
	v_mfma_f32_16x16x32_bf16 v[58:61], v[156:159], v[184:187], v[58:61]
	v_mfma_f32_16x16x32_bf16 v[46:49], v[148:151], v[196:199], v[46:49]
	v_mfma_f32_16x16x32_bf16 v[42:45], v[156:159], v[196:199], v[42:45]
	v_mfma_f32_16x16x32_bf16 v[30:33], v[148:151], v[204:207], v[30:33]
	v_mfma_f32_16x16x32_bf16 v[26:29], v[156:159], v[204:207], v[26:29]
	v_mfma_f32_16x16x32_bf16 v[14:17], v[148:151], v[212:215], v[14:17]
	v_mfma_f32_16x16x32_bf16 v[10:13], v[156:159], v[212:215], v[10:13]
	v_mfma_f32_16x16x32_bf16 v[54:57], v[164:167], v[180:183], v[54:57]
	v_mfma_f32_16x16x32_bf16 v[50:53], v[172:175], v[180:183], v[50:53]
	v_mfma_f32_16x16x32_bf16 v[38:41], v[164:167], v[188:191], v[38:41]
	v_mfma_f32_16x16x32_bf16 v[34:37], v[172:175], v[188:191], v[34:37]
	v_mfma_f32_16x16x32_bf16 v[22:25], v[164:167], v[200:203], v[22:25]
	v_mfma_f32_16x16x32_bf16 v[18:21], v[172:175], v[200:203], v[18:21]
	v_mfma_f32_16x16x32_bf16 v[6:9], v[164:167], v[208:211], v[6:9]
	v_mfma_f32_16x16x32_bf16 v[2:5], v[172:175], v[208:211], v[2:5]
	v_mfma_f32_16x16x32_bf16 v[54:57], v[168:171], v[184:187], v[54:57]
	v_mfma_f32_16x16x32_bf16 v[50:53], v[176:179], v[184:187], v[50:53]
	v_mfma_f32_16x16x32_bf16 v[38:41], v[168:171], v[196:199], v[38:41]
	v_mfma_f32_16x16x32_bf16 v[34:37], v[176:179], v[196:199], v[34:37]
	v_mfma_f32_16x16x32_bf16 v[22:25], v[168:171], v[204:207], v[22:25]
	v_mfma_f32_16x16x32_bf16 v[18:21], v[176:179], v[204:207], v[18:21]
	v_mfma_f32_16x16x32_bf16 v[6:9], v[168:171], v[212:215], v[6:9]
	v_mfma_f32_16x16x32_bf16 v[2:5], v[176:179], v[212:215], v[2:5]
	s_barrier
	ds_read_b128 v[144:147], v142
	ds_read_b128 v[148:151], v142 offset:1024
	ds_read_b128 v[152:155], v142 offset:2048
	ds_read_b128 v[156:159], v142 offset:3072
	ds_read_b128 v[164:167], v143
	ds_read_b128 v[168:171], v143 offset:1024
	ds_read_b128 v[172:175], v143 offset:2048
	ds_read_b128 v[176:179], v143 offset:3072
	s_add_u32 s14, s14, 0x200000
	s_addc_u32 s15, s15, 0
	s_mov_b32 m0, s22
	ds_read_b128 v[180:183], v141 offset:32768
	ds_read_b128 v[184:187], v141 offset:33792
	ds_read_b128 v[188:191], v141 offset:34816
	ds_read_b128 v[196:199], v141 offset:35840
	ds_read_b128 v[200:203], v141 offset:36864
	ds_read_b128 v[204:207], v141 offset:37888
	ds_read_b128 v[208:211], v141 offset:38912
	ds_read_b128 v[212:215], v141 offset:39936
	global_load_lds_dwordx4 v130, s[14:15]
	s_mov_b32 m0, s23
	s_nop 0
	global_load_lds_dwordx4 v132, s[14:15]
	s_waitcnt vmcnt(8) lgkmcnt(0)
	s_barrier
	v_mfma_f32_16x16x32_bf16 v[126:129], v[144:147], v[180:183], v[126:129]
	v_mfma_f32_16x16x32_bf16 v[122:125], v[152:155], v[180:183], v[122:125]
	v_mfma_f32_16x16x32_bf16 v[110:113], v[144:147], v[188:191], v[110:113]
	v_mfma_f32_16x16x32_bf16 v[106:109], v[152:155], v[188:191], v[106:109]
	v_mfma_f32_16x16x32_bf16 v[94:97], v[144:147], v[200:203], v[94:97]
	v_mfma_f32_16x16x32_bf16 v[90:93], v[152:155], v[200:203], v[90:93]
	v_mfma_f32_16x16x32_bf16 v[78:81], v[144:147], v[208:211], v[78:81]
	v_mfma_f32_16x16x32_bf16 v[74:77], v[152:155], v[208:211], v[74:77]
	v_mfma_f32_16x16x32_bf16 v[126:129], v[148:151], v[184:187], v[126:129]
	v_mfma_f32_16x16x32_bf16 v[122:125], v[156:159], v[184:187], v[122:125]
	v_mfma_f32_16x16x32_bf16 v[110:113], v[148:151], v[196:199], v[110:113]
	v_mfma_f32_16x16x32_bf16 v[106:109], v[156:159], v[196:199], v[106:109]
	v_mfma_f32_16x16x32_bf16 v[94:97], v[148:151], v[204:207], v[94:97]
	v_mfma_f32_16x16x32_bf16 v[90:93], v[156:159], v[204:207], v[90:93]
	v_mfma_f32_16x16x32_bf16 v[78:81], v[148:151], v[212:215], v[78:81]
	v_mfma_f32_16x16x32_bf16 v[74:77], v[156:159], v[212:215], v[74:77]
	v_mfma_f32_16x16x32_bf16 v[118:121], v[164:167], v[180:183], v[118:121]
	v_mfma_f32_16x16x32_bf16 v[114:117], v[172:175], v[180:183], v[114:117]
	v_mfma_f32_16x16x32_bf16 v[102:105], v[164:167], v[188:191], v[102:105]
	v_mfma_f32_16x16x32_bf16 v[98:101], v[172:175], v[188:191], v[98:101]
	v_mfma_f32_16x16x32_bf16 v[86:89], v[164:167], v[200:203], v[86:89]
	v_mfma_f32_16x16x32_bf16 v[82:85], v[172:175], v[200:203], v[82:85]
	v_mfma_f32_16x16x32_bf16 v[70:73], v[164:167], v[208:211], v[70:73]
	v_mfma_f32_16x16x32_bf16 v[66:69], v[172:175], v[208:211], v[66:69]
	v_mfma_f32_16x16x32_bf16 v[118:121], v[168:171], v[184:187], v[118:121]
	v_mfma_f32_16x16x32_bf16 v[114:117], v[176:179], v[184:187], v[114:117]
	v_mfma_f32_16x16x32_bf16 v[102:105], v[168:171], v[196:199], v[102:105]
	v_mfma_f32_16x16x32_bf16 v[98:101], v[176:179], v[196:199], v[98:101]
	v_mfma_f32_16x16x32_bf16 v[86:89], v[168:171], v[204:207], v[86:89]
	v_mfma_f32_16x16x32_bf16 v[82:85], v[176:179], v[204:207], v[82:85]
	v_mfma_f32_16x16x32_bf16 v[70:73], v[168:171], v[212:215], v[70:73]
	v_mfma_f32_16x16x32_bf16 v[66:69], v[176:179], v[212:215], v[66:69]
	s_barrier
	s_mov_b32 m0, s38
	s_add_u32 s12, s12, 0x200080
	s_addc_u32 s13, s13, 0
	ds_read_b128 v[180:183], v141 offset:49152
	ds_read_b128 v[184:187], v141 offset:50176
	ds_read_b128 v[188:191], v141 offset:51200
	ds_read_b128 v[196:199], v141 offset:52224
	ds_read_b128 v[200:203], v141 offset:53248
	ds_read_b128 v[204:207], v141 offset:54272
	ds_read_b128 v[208:211], v141 offset:55296
	ds_read_b128 v[212:215], v141 offset:56320
	s_add_u32 s98, s12, 0xffe00000
	s_addc_u32 s99, s13, -1
	global_load_lds_dwordx4 v130, s[98:99]
	s_mov_b32 m0, s39
	s_nop 0
	global_load_lds_dwordx4 v132, s[98:99]
	s_mov_b32 m0, s40
	s_nop 0
	global_load_lds_dwordx4 v130, s[12:13]
	s_mov_b32 m0, s41
	s_nop 0
	global_load_lds_dwordx4 v132, s[12:13]
	s_mov_b32 m0, s25
	s_nop 0
	s_add_u32 s100, s14, 0xffe00080
	s_addc_u32 s101, s15, -1
	global_load_lds_dwordx4 v130, s[100:101]
	s_mov_b32 m0, s26
	s_nop 0
	global_load_lds_dwordx4 v132, s[100:101]
	s_waitcnt vmcnt(8) lgkmcnt(0)
	s_barrier
	v_mfma_f32_16x16x32_bf16 v[62:65], v[144:147], v[180:183], v[62:65]
	v_mfma_f32_16x16x32_bf16 v[58:61], v[152:155], v[180:183], v[58:61]
	v_mfma_f32_16x16x32_bf16 v[46:49], v[144:147], v[188:191], v[46:49]
	v_mfma_f32_16x16x32_bf16 v[42:45], v[152:155], v[188:191], v[42:45]
	v_mfma_f32_16x16x32_bf16 v[30:33], v[144:147], v[200:203], v[30:33]
	v_mfma_f32_16x16x32_bf16 v[26:29], v[152:155], v[200:203], v[26:29]
	v_mfma_f32_16x16x32_bf16 v[14:17], v[144:147], v[208:211], v[14:17]
	v_mfma_f32_16x16x32_bf16 v[10:13], v[152:155], v[208:211], v[10:13]
	v_mfma_f32_16x16x32_bf16 v[62:65], v[148:151], v[184:187], v[62:65]
	v_mfma_f32_16x16x32_bf16 v[58:61], v[156:159], v[184:187], v[58:61]
	v_mfma_f32_16x16x32_bf16 v[46:49], v[148:151], v[196:199], v[46:49]
	v_mfma_f32_16x16x32_bf16 v[42:45], v[156:159], v[196:199], v[42:45]
	v_mfma_f32_16x16x32_bf16 v[30:33], v[148:151], v[204:207], v[30:33]
	v_mfma_f32_16x16x32_bf16 v[26:29], v[156:159], v[204:207], v[26:29]
	v_mfma_f32_16x16x32_bf16 v[14:17], v[148:151], v[212:215], v[14:17]
	v_mfma_f32_16x16x32_bf16 v[10:13], v[156:159], v[212:215], v[10:13]
	v_mfma_f32_16x16x32_bf16 v[54:57], v[164:167], v[180:183], v[54:57]
	v_mfma_f32_16x16x32_bf16 v[50:53], v[172:175], v[180:183], v[50:53]
	v_mfma_f32_16x16x32_bf16 v[38:41], v[164:167], v[188:191], v[38:41]
	v_mfma_f32_16x16x32_bf16 v[34:37], v[172:175], v[188:191], v[34:37]
	v_mfma_f32_16x16x32_bf16 v[22:25], v[164:167], v[200:203], v[22:25]
	v_mfma_f32_16x16x32_bf16 v[18:21], v[172:175], v[200:203], v[18:21]
	v_mfma_f32_16x16x32_bf16 v[6:9], v[164:167], v[208:211], v[6:9]
	v_mfma_f32_16x16x32_bf16 v[2:5], v[172:175], v[208:211], v[2:5]
	v_mfma_f32_16x16x32_bf16 v[54:57], v[168:171], v[184:187], v[54:57]
	v_mfma_f32_16x16x32_bf16 v[50:53], v[176:179], v[184:187], v[50:53]
	v_mfma_f32_16x16x32_bf16 v[38:41], v[168:171], v[196:199], v[38:41]
	v_mfma_f32_16x16x32_bf16 v[34:37], v[176:179], v[196:199], v[34:37]
	v_mfma_f32_16x16x32_bf16 v[22:25], v[168:171], v[204:207], v[22:25]
	v_mfma_f32_16x16x32_bf16 v[18:21], v[176:179], v[204:207], v[18:21]
	v_mfma_f32_16x16x32_bf16 v[6:9], v[168:171], v[212:215], v[6:9]
	v_mfma_f32_16x16x32_bf16 v[2:5], v[176:179], v[212:215], v[2:5]
	s_barrier
	s_add_i32 s29, s29, 2
	s_add_u32 s10, s10, 0x100
	s_addc_u32 s11, s11, 0
	s_cmpk_lt_u32 s29, 0x7e
	s_cbranch_scc1 .LBB0_1031
	s_setprio 0
	s_waitcnt vmcnt(0)
	s_cmpk_gt_u32 s19, 0xff
	s_cbranch_scc1 .LBB0_1034
	s_barrier
